# SB stage bodies: maskless copy for tiles fully below the diagonal (branch on wave-uniform v_cmp result); drops 96 mask VALU per non-diagonal wave-stage
# speedup vs baseline: 1.0286x; 1.0026x over previous
; DI unsigned pk_bf16(float lo, float hi) { f32x2 v = {lo, hi}; bf2_t b = __builtin_convertvector(v, bf2_t); return __builtin_bit_cast(unsigned, b); }
; DI float bf_lo(unsigned u) { return __uint_as_float(u << 16); }
; DI float bf_hi(unsigned u) { return __uint_as_float(u & 0xffff0000u); }
; DI int crow(int i, int h) { return (i & 3) + 8 * (i >> 2) + 4 * h; }
; DI float fast_exp2(float x) { return __builtin_amdgcn_exp2f(x); }
; DI float fast_log2(float x) { return __builtin_amdgcn_logf(x); }
; #define AT_LOAD(SET, IT) { const int kl_ = AT_KB(IT); \
;     _Pragma("unroll") for (int i = 0; i < KPT; ++i) kreg[SET][i] = *(const u32x4*)(Kg + (size_t)kl_ * DQK + (tid + 256 * i) * 8); \
;     _Pragma("unroll") for (int i = 0; i < 2; ++i) vreg[SET][i] = *(const u32x4*)(Vg + (size_t)kl_ * 64 + (tid + 256 * i) * 8); \
;     __builtin_amdgcn_sched_barrier(0); }
; template <int DQK, bool SB, bool SMAX>
; DI void attn_item(const Params& p, char* smem, int bh, int qb, float Mb) {
;     ...
;     AT_WRITE(0, st2 ^ 1)
;     AT_LOAD(0, (it + 2 < nt) ? it + 2 : nt - 1)
;     if (active) {
;       const bool diag = (kb0 + 64 > qw0);
;       bf16x8 pk[4];
;     ...
;           for (int i2 = 0; i2 < 8; ++i2) {
;             float lk[2];
; #pragma unroll
;             for (int e = 0; e < 2; ++e) {
;               const int i = 2 * i2 + e;
;               const float z = fminf(st[kb][i], 100.f);
;               const int key = kb0 + kb * 32 + crow(i, h);
;               const bool valid = !diag || (key < query);
;               float l = -fast_log2(1.f + fast_exp2(z));
;               l = valid ? l : 0.f;
;               lk[e] = l;
;               tsum += l;
;               ca[kb][i] = z + carry;
;             }
;             const unsigned hp = pk_bf16(lk[0], lk[1]);
;             const unsigned lp = pk_bf16(lk[0] - bf_lo(hp), lk[1] - bf_hi(hp));
;             const int kk = kb * 2 + (i2 >> 2), w = i2 & 3;
;             hi[kk][2 * w] = (short)(hp & 0xffffu); hi[kk][2 * w + 1] = (short)(hp >> 16);
;             lo[kk][2 * w] = (short)(lp & 0xffffu); lo[kk][2 * w + 1] = (short)(lp >> 16);
;           }
.LBB0_435:
	s_or_b64 exec, exec, s[2:3]
	s_cmp_lt_u32 s4, s1
	s_cselect_b32 s2, s78, 0
	s_ashr_i32 s3, s2, 31
	s_lshl_b64 s[2:3], s[2:3], 7
	v_lshl_add_u64 v[80:81], v[148:149], 0, s[2:3]
	s_waitcnt vmcnt(3)
	ds_write_b128 v203, v[120:123] offset:9216
	s_waitcnt vmcnt(2)
	ds_write_b128 v204, v[124:127] offset:9216
	s_waitcnt vmcnt(1)
	ds_write_b128 v203, v[128:131] offset:27648
	s_waitcnt vmcnt(0)
	ds_write_b128 v204, v[132:135] offset:27648
	v_add_co_u32_e32 v82, vcc, 0x1000, v80
	s_nop 1
	v_addc_co_u32_e32 v83, vcc, 0, v81, vcc
	global_load_dwordx4 v[120:123], v[80:81], off
	global_load_dwordx4 v[124:127], v[82:83], off
	v_lshl_add_u64 v[80:81], v[150:151], 0, s[2:3]
	v_add_co_u32_e32 v82, vcc, 0x1000, v80
	s_nop 1
	v_addc_co_u32_e32 v83, vcc, 0, v81, vcc
	global_load_dwordx4 v[128:131], v[80:81], off
	global_load_dwordx4 v[132:135], v[82:83], off
	s_and_saveexec_b64 s[80:81], s[12:13]
	s_cbranch_execz .LBB0_437
	v_cmp_le_i32_e64 s[44:45], s14, v181
	s_nop 0
	s_cmp_eq_u64 s[44:45], exec
	s_cbranch_scc1 .Lsbf_1
	s_nop 0
	v_add_u32_e32 v143, s78, v197
	v_min_f32_e32 v84, 0x42c80000, v64
	s_nop 0
	v_exp_f32_e32 v64, v84
	v_min_f32_e32 v85, 0x42c80000, v65
	v_add_u32_e32 v65, 0x81, v143
	v_cmp_lt_i32_e64 s[2:3], v65, v176
	v_exp_f32_e32 v65, v85
	v_add_f32_e32 v64, 1.0, v64
	v_log_f32_e32 v64, v64
	v_add_u32_e32 v80, 0x80, v143
	v_add_f32_e32 v65, 1.0, v65
	v_log_f32_e32 v65, v65
	v_cmp_le_i32_e64 s[44:45], s14, v181
	v_cmp_lt_i32_e32 vcc, v80, v176
	s_or_b64 vcc, s[44:45], vcc
	s_or_b64 s[12:13], s[44:45], s[2:3]
	v_cndmask_b32_e64 v64, 0, -v64, vcc
	v_add_f32_e32 v80, 0, v64
	v_cndmask_b32_e64 v65, 0, -v65, s[12:13]
	v_add_f32_e32 v81, v65, v80
	v_cvt_pk_bf16_f32 v80, v64, v65
	v_lshlrev_b32_e32 v82, 16, v80
	v_sub_f32_e32 v64, v64, v82
	v_and_b32_e32 v82, 0xffff0000, v80
	v_sub_f32_e32 v65, v65, v82
	v_cvt_pk_bf16_f32 v64, v64, v65
	s_nop 0
	v_min_f32_e32 v86, 0x42c80000, v66
	v_add_u32_e32 v65, 0x82, v143
	s_nop 0
	v_cmp_lt_i32_e64 s[2:3], v65, v176
	v_min_f32_e32 v87, 0x42c80000, v67
	v_add_u32_e32 v67, 0x83, v143
	s_or_b64 s[14:15], s[44:45], s[2:3]
	v_exp_f32_e32 v65, v86
	v_cmp_lt_i32_e64 s[2:3], v67, v176
	v_exp_f32_e32 v67, v87
	s_or_b64 s[16:17], s[44:45], s[2:3]
	v_add_f32_e32 v65, 1.0, v65
	v_log_f32_e32 v65, v65
	v_add_f32_e32 v67, 1.0, v67
	v_log_f32_e32 v67, v67
	s_nop 0
	v_cndmask_b32_e64 v65, 0, -v65, s[14:15]
	v_add_f32_e32 v66, v65, v81
	v_cndmask_b32_e64 v67, 0, -v67, s[16:17]
	v_cvt_pk_bf16_f32 v81, v65, v67
	v_lshlrev_b32_e32 v82, 16, v81
	v_sub_f32_e32 v65, v65, v82
	v_and_b32_e32 v82, 0xffff0000, v81
	v_add_f32_e32 v66, v67, v66
	v_sub_f32_e32 v67, v67, v82
	v_cvt_pk_bf16_f32 v65, v65, v67
	s_nop 0
	v_min_f32_e32 v88, 0x42c80000, v68
	v_add_u32_e32 v67, 0x88, v143
	s_nop 0
	v_cmp_lt_i32_e64 s[2:3], v67, v176
	v_min_f32_e32 v89, 0x42c80000, v69
	v_add_u32_e32 v68, 0x89, v143
	s_or_b64 s[18:19], s[44:45], s[2:3]
	v_exp_f32_e32 v67, v88
	v_cmp_lt_i32_e64 s[2:3], v68, v176
	v_exp_f32_e32 v68, v89
	s_or_b64 s[20:21], s[44:45], s[2:3]
	v_add_f32_e32 v67, 1.0, v67
	v_log_f32_e32 v67, v67
	v_add_f32_e32 v68, 1.0, v68
	v_log_f32_e32 v68, v68
	s_nop 0
	v_cndmask_b32_e64 v67, 0, -v67, s[18:19]
	v_add_f32_e32 v66, v67, v66
	v_cndmask_b32_e64 v68, 0, -v68, s[20:21]
	v_cvt_pk_bf16_f32 v82, v67, v68
	v_add_f32_e32 v69, v68, v66
	v_lshlrev_b32_e32 v66, 16, v82
	v_sub_f32_e32 v66, v67, v66
	v_and_b32_e32 v67, 0xffff0000, v82
	v_sub_f32_e32 v67, v68, v67
	v_cvt_pk_bf16_f32 v66, v66, v67
	s_nop 0
	v_min_f32_e32 v90, 0x42c80000, v70
	v_add_u32_e32 v67, 0x8a, v143
	v_cmp_lt_i32_e64 s[2:3], v67, v176
	v_exp_f32_e32 v67, v90
	s_or_b64 s[22:23], s[44:45], s[2:3]
	v_min_f32_e32 v156, 0x42c80000, v48
	v_min_f32_e32 v157, 0x42c80000, v49
	v_add_f32_e32 v67, 1.0, v67
	v_log_f32_e32 v67, v67
	v_add_u32_e32 v49, 0xa1, v143
	v_exp_f32_e32 v48, v156
	s_mov_b32 s97, s96
	v_cndmask_b32_e64 v67, 0, -v67, s[22:23]
	v_add_f32_e32 v68, v67, v69
	s_nop 0
	v_min_f32_e32 v91, 0x42c80000, v71
	v_add_u32_e32 v69, 0x8b, v143
	v_cmp_lt_i32_e64 s[2:3], v69, v176
	v_exp_f32_e32 v69, v91
	s_or_b64 s[24:25], s[44:45], s[2:3]
	v_add_f32_e32 v48, 1.0, v48
	v_log_f32_e32 v48, v48
	v_add_f32_e32 v69, 1.0, v69
	v_log_f32_e32 v69, v69
	s_mov_b32 s98, s96
	s_mov_b32 s99, s96
	v_cndmask_b32_e64 v69, 0, -v69, s[24:25]
	v_cvt_pk_bf16_f32 v83, v67, v69
	v_lshlrev_b32_e32 v70, 16, v83
	v_sub_f32_e32 v67, v67, v70
	v_and_b32_e32 v70, 0xffff0000, v83
	v_add_f32_e32 v68, v69, v68
	v_sub_f32_e32 v69, v69, v70
	v_cvt_pk_bf16_f32 v67, v67, v69
	s_nop 0
	v_min_f32_e32 v92, 0x42c80000, v72
	v_add_u32_e32 v69, 0x90, v143
	s_nop 0
	v_cmp_lt_i32_e64 s[2:3], v69, v176
	v_min_f32_e32 v93, 0x42c80000, v73
	v_add_u32_e32 v70, 0x91, v143
	s_or_b64 s[26:27], s[44:45], s[2:3]
	v_exp_f32_e32 v69, v92
	v_cmp_lt_i32_e64 s[2:3], v70, v176
	v_exp_f32_e32 v70, v93
	s_or_b64 s[28:29], s[44:45], s[2:3]
	v_add_f32_e32 v69, 1.0, v69
	v_log_f32_e32 v69, v69
	v_add_f32_e32 v70, 1.0, v70
	v_log_f32_e32 v70, v70
	v_cndmask_b32_e64 v69, 0, -v69, s[26:27]
	v_add_f32_e32 v68, v69, v68
	v_cndmask_b32_e64 v70, 0, -v70, s[28:29]
	v_cvt_pk_bf16_f32 v72, v69, v70
	v_add_f32_e32 v71, v70, v68
	v_lshlrev_b32_e32 v68, 16, v72
	v_sub_f32_e32 v68, v69, v68
	v_and_b32_e32 v69, 0xffff0000, v72
	v_sub_f32_e32 v69, v70, v69
	v_cvt_pk_bf16_f32 v68, v68, v69
	s_nop 0
	v_min_f32_e32 v94, 0x42c80000, v74
	v_add_u32_e32 v69, 0x92, v143
	v_cmp_lt_i32_e64 s[2:3], v69, v176
	v_exp_f32_e32 v69, v94
	s_or_b64 s[30:31], s[44:45], s[2:3]
	v_add_f32_e32 v69, 1.0, v69
	v_log_f32_e32 v69, v69
	s_nop 0
	v_cndmask_b32_e64 v69, 0, -v69, s[30:31]
	v_add_f32_e32 v70, v69, v71
	s_nop 0
	v_min_f32_e32 v95, 0x42c80000, v75
	v_add_u32_e32 v71, 0x93, v143
; DI unsigned pk_bf16(float lo, float hi) { f32x2 v = {lo, hi}; bf2_t b = __builtin_convertvector(v, bf2_t); return __builtin_bit_cast(unsigned, b); }
; DI float bf_lo(unsigned u) { return __uint_as_float(u << 16); }
; DI float bf_hi(unsigned u) { return __uint_as_float(u & 0xffff0000u); }
; DI int crow(int i, int h) { return (i & 3) + 8 * (i >> 2) + 4 * h; }
; DI float fast_exp2(float x) { return __builtin_amdgcn_exp2f(x); }
; DI float fast_log2(float x) { return __builtin_amdgcn_logf(x); }
; template <int DQK, bool SB, bool SMAX>
; DI void attn_item(const Params& p, char* smem, int bh, int qb, float Mb) {
;     ...
;           for (int i2 = 0; i2 < 8; ++i2) {
;             float lk[2];
; #pragma unroll
;             for (int e = 0; e < 2; ++e) {
;               const int i = 2 * i2 + e;
;               const float z = fminf(st[kb][i], 100.f);
;               const int key = kb0 + kb * 32 + crow(i, h);
;               const bool valid = !diag || (key < query);
;               float l = -fast_log2(1.f + fast_exp2(z));
;               l = valid ? l : 0.f;
;               lk[e] = l;
;               tsum += l;
;               ca[kb][i] = z + carry;
;             }
;             const unsigned hp = pk_bf16(lk[0], lk[1]);
;             const unsigned lp = pk_bf16(lk[0] - bf_lo(hp), lk[1] - bf_hi(hp));
;             const int kk = kb * 2 + (i2 >> 2), w = i2 & 3;
;             hi[kk][2 * w] = (short)(hp & 0xffffu); hi[kk][2 * w + 1] = (short)(hp >> 16);
;             lo[kk][2 * w] = (short)(lp & 0xffffu); lo[kk][2 * w + 1] = (short)(lp >> 16);
;           }
	v_cmp_lt_i32_e64 s[2:3], v71, v176
	v_exp_f32_e32 v71, v95
	s_or_b64 s[34:35], s[44:45], s[2:3]
	v_add_f32_e32 v71, 1.0, v71
	v_log_f32_e32 v71, v71
	s_nop 0
	v_cndmask_b32_e64 v71, 0, -v71, s[34:35]
	v_cvt_pk_bf16_f32 v73, v69, v71
	v_lshlrev_b32_e32 v74, 16, v73
	v_sub_f32_e32 v69, v69, v74
	v_and_b32_e32 v74, 0xffff0000, v73
	v_add_f32_e32 v70, v71, v70
	v_sub_f32_e32 v71, v71, v74
	v_cvt_pk_bf16_f32 v69, v69, v71
	s_nop 0
	v_min_f32_e32 v154, 0x42c80000, v76
	v_add_u32_e32 v71, 0x98, v143
	s_nop 0
	v_cmp_lt_i32_e64 s[2:3], v71, v176
	v_min_f32_e32 v155, 0x42c80000, v77
	v_add_u32_e32 v74, 0x99, v143
	s_or_b64 s[36:37], s[44:45], s[2:3]
	v_exp_f32_e32 v71, v154
	v_cmp_lt_i32_e64 s[2:3], v74, v176
	v_exp_f32_e32 v74, v155
	s_or_b64 s[38:39], s[44:45], s[2:3]
	v_add_f32_e32 v71, 1.0, v71
	v_log_f32_e32 v71, v71
	v_add_f32_e32 v74, 1.0, v74
	v_log_f32_e32 v74, v74
	v_cndmask_b32_e64 v71, 0, -v71, s[36:37]
	v_add_f32_e32 v70, v71, v70
	v_cndmask_b32_e64 v75, 0, -v74, s[38:39]
	v_cvt_pk_bf16_f32 v74, v71, v75
	v_add_f32_e32 v76, v75, v70
	v_lshlrev_b32_e32 v70, 16, v74
	v_sub_f32_e32 v70, v71, v70
	v_and_b32_e32 v71, 0xffff0000, v74
	v_sub_f32_e32 v71, v75, v71
	v_cvt_pk_bf16_f32 v70, v70, v71
	s_nop 0
	v_min_f32_e32 v158, 0x42c80000, v78
	v_add_u32_e32 v71, 0x9a, v143
	v_cmp_lt_i32_e64 s[2:3], v71, v176
	v_exp_f32_e32 v71, v158
	s_or_b64 s[40:41], s[44:45], s[2:3]
	v_add_f32_e32 v71, 1.0, v71
	v_log_f32_e32 v71, v71
	s_nop 0
	v_cndmask_b32_e64 v71, 0, -v71, s[40:41]
	v_add_f32_e32 v75, v71, v76
	s_nop 0
	v_min_f32_e32 v159, 0x42c80000, v79
	v_add_u32_e32 v76, 0x9b, v143
	v_cmp_lt_i32_e64 s[2:3], v76, v176
	v_exp_f32_e32 v76, v159
	s_or_b64 s[42:43], s[44:45], s[2:3]
	v_add_f32_e32 v76, 1.0, v76
	v_log_f32_e32 v76, v76
	s_nop 0
	v_cndmask_b32_e64 v76, 0, -v76, s[42:43]
	v_add_f32_e32 v77, v76, v75
	v_cvt_pk_bf16_f32 v75, v71, v76
	v_lshlrev_b32_e32 v78, 16, v75
	v_sub_f32_e32 v71, v71, v78
	v_and_b32_e32 v78, 0xffff0000, v75
	v_sub_f32_e32 v76, v76, v78
	v_cvt_pk_bf16_f32 v71, v71, v76
	v_add_u32_e32 v76, 0xa0, v143
	v_cmp_lt_i32_e64 s[2:3], v76, v176
	s_or_b64 s[46:47], s[44:45], s[2:3]
	v_cmp_lt_i32_e64 s[2:3], v49, v176
	v_exp_f32_e32 v49, v157
	s_or_b64 s[48:49], s[44:45], s[2:3]
	v_cndmask_b32_e64 v48, 0, -v48, s[46:47]
	v_add_f32_e32 v76, v48, v77
	v_add_f32_e32 v49, 1.0, v49
	v_log_f32_e32 v49, v49
	s_nop 0
	v_cndmask_b32_e64 v49, 0, -v49, s[48:49]
	v_cvt_pk_bf16_f32 v136, v48, v49
	v_add_f32_e32 v77, v49, v76
	v_lshlrev_b32_e32 v76, 16, v136
	v_sub_f32_e32 v48, v48, v76
	v_and_b32_e32 v76, 0xffff0000, v136
	v_sub_f32_e32 v49, v49, v76
	v_cvt_pk_bf16_f32 v76, v48, v49
	s_nop 0
	v_min_f32_e32 v160, 0x42c80000, v50
	v_add_u32_e32 v48, 0xa2, v143
	s_nop 0
	v_cmp_lt_i32_e64 s[2:3], v48, v176
	v_min_f32_e32 v161, 0x42c80000, v51
	v_add_u32_e32 v50, 0xa3, v143
	s_or_b64 s[50:51], s[44:45], s[2:3]
	v_exp_f32_e32 v48, v160
	v_cmp_lt_i32_e64 s[2:3], v50, v176
	v_exp_f32_e32 v50, v161
	s_or_b64 s[52:53], s[44:45], s[2:3]
	v_add_f32_e32 v48, 1.0, v48
	v_log_f32_e32 v48, v48
	v_add_f32_e32 v50, 1.0, v50
	v_log_f32_e32 v50, v50
	v_cndmask_b32_e64 v48, 0, -v48, s[50:51]
	v_add_f32_e32 v49, v48, v77
	v_cndmask_b32_e64 v50, 0, -v50, s[52:53]
	v_cvt_pk_bf16_f32 v137, v48, v50
	v_lshlrev_b32_e32 v51, 16, v137
	v_sub_f32_e32 v48, v48, v51
	v_and_b32_e32 v51, 0xffff0000, v137
	v_add_f32_e32 v49, v50, v49
	v_sub_f32_e32 v50, v50, v51
	v_cvt_pk_bf16_f32 v77, v48, v50
	s_nop 0
	v_min_f32_e32 v162, 0x42c80000, v52
	v_add_u32_e32 v48, 0xa8, v143
	s_nop 0
	v_cmp_lt_i32_e64 s[2:3], v48, v176
	v_min_f32_e32 v163, 0x42c80000, v53
	v_add_u32_e32 v50, 0xa9, v143
	s_or_b64 s[54:55], s[44:45], s[2:3]
	v_exp_f32_e32 v48, v162
	v_cmp_lt_i32_e64 s[2:3], v50, v176
	v_exp_f32_e32 v50, v163
	s_or_b64 s[56:57], s[44:45], s[2:3]
	v_add_f32_e32 v48, 1.0, v48
	v_log_f32_e32 v48, v48
	v_add_f32_e32 v50, 1.0, v50
	v_log_f32_e32 v50, v50
	v_pk_add_f32 v[52:53], v[152:153], v[88:89] op_sel_hi:[0,1]
	v_cndmask_b32_e64 v48, 0, -v48, s[54:55]
	v_add_f32_e32 v49, v48, v49
	v_cndmask_b32_e64 v50, 0, -v50, s[56:57]
	v_cvt_pk_bf16_f32 v138, v48, v50
	v_lshlrev_b32_e32 v51, 16, v138
	v_sub_f32_e32 v48, v48, v51
	v_and_b32_e32 v51, 0xffff0000, v138
	v_add_f32_e32 v49, v50, v49
	v_sub_f32_e32 v50, v50, v51
	v_cvt_pk_bf16_f32 v78, v48, v50
	s_nop 0
	v_min_f32_e32 v164, 0x42c80000, v54
	v_add_u32_e32 v48, 0xaa, v143
	s_nop 0
	v_cmp_lt_i32_e64 s[2:3], v48, v176
	v_min_f32_e32 v165, 0x42c80000, v55
	v_add_u32_e32 v50, 0xab, v143
	s_or_b64 s[58:59], s[44:45], s[2:3]
	v_exp_f32_e32 v48, v164
	v_cmp_lt_i32_e64 s[2:3], v50, v176
	v_exp_f32_e32 v50, v165
	s_or_b64 s[60:61], s[44:45], s[2:3]
	v_add_f32_e32 v48, 1.0, v48
	v_log_f32_e32 v48, v48
	v_add_f32_e32 v50, 1.0, v50
	v_log_f32_e32 v50, v50
	v_pk_add_f32 v[54:55], v[152:153], v[90:91] op_sel_hi:[0,1]
	v_cndmask_b32_e64 v48, 0, -v48, s[58:59]
	v_add_f32_e32 v49, v48, v49
	v_cndmask_b32_e64 v50, 0, -v50, s[60:61]
	v_cvt_pk_bf16_f32 v139, v48, v50
	v_lshlrev_b32_e32 v51, 16, v139
	v_sub_f32_e32 v48, v48, v51
	v_and_b32_e32 v51, 0xffff0000, v139
	v_add_f32_e32 v49, v50, v49
	v_sub_f32_e32 v50, v50, v51
	v_cvt_pk_bf16_f32 v79, v48, v50
	s_nop 0
	v_min_f32_e32 v166, 0x42c80000, v56
	v_add_u32_e32 v48, 0xb0, v143
	s_nop 0
	v_cmp_lt_i32_e64 s[2:3], v48, v176
	v_min_f32_e32 v167, 0x42c80000, v57
	v_add_u32_e32 v50, 0xb1, v143
	s_or_b64 s[62:63], s[44:45], s[2:3]
	v_exp_f32_e32 v48, v166
	v_cmp_lt_i32_e64 s[2:3], v50, v176
	v_exp_f32_e32 v50, v167
	s_or_b64 s[64:65], s[44:45], s[2:3]
	v_add_f32_e32 v48, 1.0, v48
	v_log_f32_e32 v48, v48
	v_add_f32_e32 v50, 1.0, v50
	v_log_f32_e32 v50, v50
	v_pk_add_f32 v[56:57], v[152:153], v[92:93] op_sel_hi:[0,1]
; #define MFMA32(a, b, c) __builtin_amdgcn_mfma_f32_32x32x16_bf16((a), (b), (c), 0, 0, 0)
; DI unsigned pk_bf16(float lo, float hi) { f32x2 v = {lo, hi}; bf2_t b = __builtin_convertvector(v, bf2_t); return __builtin_bit_cast(unsigned, b); }
; DI int crow(int i, int h) { return (i & 3) + 8 * (i >> 2) + 4 * h; }
; DI float fast_exp2(float x) { return __builtin_amdgcn_exp2f(x); }
; template <int DQK, bool SB, bool SMAX>
; DI void attn_item(const Params& p, char* smem, int bh, int qb, float Mb) {
;     ...
;         tsum += other_half(tsum);
; #pragma unroll
;         for (int s = 0; s < 2; ++s) {
;           ca[0] = MFMA32(tri[s], hi[s], ca[0]);
;           ca[0] = MFMA32(tri[s], lo[s], ca[0]);
;           ca[0] = MFMA32(ones, hi[2 + s], ca[0]);
;           ca[0] = MFMA32(ones, lo[2 + s], ca[0]);
;           ca[1] = MFMA32(tri[s], hi[2 + s], ca[1]);
;           ca[1] = MFMA32(tri[s], lo[2 + s], ca[1]);
;         }
; #pragma unroll
;         for (int kb = 0; kb < 2; ++kb)
; #pragma unroll
;           for (int i = 0; i < 16; ++i) {
;             const int key = kb0 + kb * 32 + crow(i, h);
;             const bool valid = !diag || (key < query);
;             st[kb][i] = valid ? fast_exp2(ca[kb][i]) : 0.f;
;           }
;         carry += tsum;
;     ...
; #pragma unroll
;           for (int e = 0; e < 4; ++e) w[e] = pk_bf16(st[kb][8 * s + 2 * e], st[kb][8 * s + 2 * e + 1]);
;           pk[kb * 2 + s] = __builtin_bit_cast(bf16x8, w);
;         }
; #pragma unroll
;       for (int kk = 0; kk < 4; ++kk)
; #pragma unroll
;         for (int db = 0; db < 2; ++db) {
;           const s16x4 v0 = __builtin_amdgcn_ds_read_tr16_b64_v4i16((lds_s16x4*)(vc + voff + (16 * kk) * VSTR + 32 * db));
;           const s16x4 v1 = __builtin_amdgcn_ds_read_tr16_b64_v4i16((lds_s16x4*)(vc + voff + (16 * kk + 8) * VSTR + 32 * db));
;           const bf16x8 vf = __builtin_shufflevector(v0, v1, 0, 1, 2, 3, 4, 5, 6, 7);
;           O[db] = MFMA32(vf, pk[kk], O[db]);
	v_cndmask_b32_e64 v48, 0, -v48, s[62:63]
	v_add_f32_e32 v49, v48, v49
	v_cndmask_b32_e64 v50, 0, -v50, s[64:65]
	v_cvt_pk_bf16_f32 v140, v48, v50
	v_lshlrev_b32_e32 v51, 16, v140
	v_sub_f32_e32 v48, v48, v51
	v_and_b32_e32 v51, 0xffff0000, v140
	v_add_f32_e32 v49, v50, v49
	v_sub_f32_e32 v50, v50, v51
	v_cvt_pk_bf16_f32 v144, v48, v50
	s_nop 0
	v_min_f32_e32 v168, 0x42c80000, v58
	v_add_u32_e32 v48, 0xb2, v143
	s_nop 0
	v_cmp_lt_i32_e64 s[2:3], v48, v176
	v_min_f32_e32 v169, 0x42c80000, v59
	v_add_u32_e32 v50, 0xb3, v143
	s_or_b64 s[66:67], s[44:45], s[2:3]
	v_exp_f32_e32 v48, v168
	v_cmp_lt_i32_e64 s[2:3], v50, v176
	v_exp_f32_e32 v50, v169
	s_or_b64 s[68:69], s[44:45], s[2:3]
	v_add_f32_e32 v48, 1.0, v48
	v_log_f32_e32 v48, v48
	v_add_f32_e32 v50, 1.0, v50
	v_log_f32_e32 v50, v50
	v_pk_add_f32 v[58:59], v[152:153], v[94:95] op_sel_hi:[0,1]
	v_cndmask_b32_e64 v48, 0, -v48, s[66:67]
	v_add_f32_e32 v49, v48, v49
	v_cndmask_b32_e64 v50, 0, -v50, s[68:69]
	v_cvt_pk_bf16_f32 v141, v48, v50
	v_lshlrev_b32_e32 v51, 16, v141
	v_sub_f32_e32 v48, v48, v51
	v_and_b32_e32 v51, 0xffff0000, v141
	v_add_f32_e32 v49, v50, v49
	v_sub_f32_e32 v50, v50, v51
	v_cvt_pk_bf16_f32 v145, v48, v50
	s_nop 0
	v_min_f32_e32 v170, 0x42c80000, v60
	v_add_u32_e32 v48, 0xb8, v143
	s_nop 0
	v_cmp_lt_i32_e64 s[2:3], v48, v176
	v_min_f32_e32 v171, 0x42c80000, v61
	v_add_u32_e32 v50, 0xb9, v143
	s_or_b64 s[70:71], s[44:45], s[2:3]
	v_exp_f32_e32 v48, v170
	v_cmp_lt_i32_e64 s[2:3], v50, v176
	v_exp_f32_e32 v50, v171
	s_or_b64 s[72:73], s[44:45], s[2:3]
	v_add_f32_e32 v48, 1.0, v48
	v_log_f32_e32 v48, v48
	v_add_f32_e32 v50, 1.0, v50
	v_log_f32_e32 v50, v50
	v_pk_add_f32 v[60:61], v[152:153], v[154:155] op_sel_hi:[0,1]
	v_cndmask_b32_e64 v48, 0, -v48, s[70:71]
	v_add_f32_e32 v49, v48, v49
	v_cndmask_b32_e64 v50, 0, -v50, s[72:73]
	v_cvt_pk_bf16_f32 v142, v48, v50
	v_lshlrev_b32_e32 v51, 16, v142
	v_sub_f32_e32 v48, v48, v51
	v_and_b32_e32 v51, 0xffff0000, v142
	v_add_f32_e32 v49, v50, v49
	v_sub_f32_e32 v50, v50, v51
	v_cvt_pk_bf16_f32 v146, v48, v50
	s_nop 0
	v_min_f32_e32 v182, 0x42c80000, v62
	v_add_u32_e32 v48, 0xba, v143
	s_nop 0
	v_cmp_lt_i32_e64 s[2:3], v48, v176
	v_min_f32_e32 v183, 0x42c80000, v63
	v_add_u32_e32 v50, 0xbb, v143
	s_or_b64 s[74:75], s[44:45], s[2:3]
	v_exp_f32_e32 v48, v182
	v_cmp_lt_i32_e64 s[2:3], v50, v176
	v_exp_f32_e32 v50, v183
	s_or_b64 s[44:45], s[44:45], s[2:3]
	v_add_f32_e32 v48, 1.0, v48
	v_log_f32_e32 v48, v48
	v_add_f32_e32 v50, 1.0, v50
	v_log_f32_e32 v50, v50
	v_pk_add_f32 v[62:63], v[152:153], v[158:159] op_sel_hi:[0,1]
	v_cndmask_b32_e64 v48, 0, -v48, s[74:75]
	v_add_f32_e32 v49, v48, v49
	v_cndmask_b32_e64 v50, 0, -v50, s[44:45]
	v_cvt_pk_bf16_f32 v143, v48, v50
	v_add_f32_e32 v184, v50, v49
	v_lshlrev_b32_e32 v49, 16, v143
	v_sub_f32_e32 v48, v48, v49
	v_and_b32_e32 v49, 0xffff0000, v143
	v_sub_f32_e32 v49, v50, v49
	v_cvt_pk_bf16_f32 v147, v48, v49
	v_mov_b32_e32 v48, v184
	v_mov_b32_e32 v49, v184
	s_nop 1
	v_permlane32_swap_b32_e32 v48, v49
	v_cndmask_b32_e64 v185, v48, v49, s[8:9]
	v_pk_add_f32 v[50:51], v[152:153], v[86:87] op_sel_hi:[0,1]
	v_pk_add_f32 v[48:49], v[152:153], v[84:85] op_sel_hi:[0,1]
	v_pk_add_f32 v[94:95], v[152:153], v[182:183] op_sel_hi:[0,1]
	v_pk_add_f32 v[92:93], v[152:153], v[170:171] op_sel_hi:[0,1]
	v_mfma_f32_32x32x16_bf16 v[48:63], v[96:99], v[80:83], v[48:63]
	v_add_f32_e64 v90, v152, v168
	v_add_f32_e64 v91, v152, v169
	v_add_f32_e64 v88, v152, v166
	v_add_f32_e64 v89, v152, v167
	v_add_f32_e64 v86, v152, v164
	v_add_f32_e64 v87, v152, v165
	v_pk_add_f32 v[84:85], v[152:153], v[162:163] op_sel_hi:[0,1]
	v_pk_add_f32 v[82:83], v[152:153], v[160:161] op_sel_hi:[0,1]
	v_pk_add_f32 v[80:81], v[152:153], v[156:157] op_sel_hi:[0,1]
	v_mfma_f32_32x32x16_bf16 v[48:63], v[96:99], v[64:67], v[48:63]
	v_mov_b64_e32 v[64:65], s[96:97]
	v_mov_b64_e32 v[66:67], s[98:99]
	s_nop 1
	v_mfma_f32_32x32x16_bf16 v[48:63], v[64:67], v[136:139], v[48:63]
	v_mfma_f32_32x32x16_bf16 v[48:63], v[64:67], v[76:79], v[48:63]
	v_mfma_f32_32x32x16_bf16 v[48:63], v[100:103], v[72:75], v[48:63]
	v_mfma_f32_32x32x16_bf16 v[48:63], v[100:103], v[68:71], v[48:63]
	v_mfma_f32_32x32x16_bf16 v[48:63], v[64:67], v[140:143], v[48:63]
	v_mfma_f32_32x32x16_bf16 v[48:63], v[64:67], v[144:147], v[48:63]
	v_mfma_f32_32x32x16_bf16 v[80:95], v[96:99], v[136:139], v[80:95]
	s_nop 10
	v_exp_f32_e32 v48, v48
	s_nop 0
	v_cndmask_b32_e32 v64, 0, v48, vcc
	v_exp_f32_e32 v48, v49
	v_mfma_f32_32x32x16_bf16 v[80:95], v[96:99], v[76:79], v[80:95]
	v_cndmask_b32_e64 v65, 0, v48, s[12:13]
	v_exp_f32_e32 v48, v50
	s_nop 0
	v_cndmask_b32_e64 v66, 0, v48, s[14:15]
	v_exp_f32_e32 v48, v51
	v_mfma_f32_32x32x16_bf16 v[80:95], v[100:103], v[140:143], v[80:95]
	v_add_u32_e32 v141, v198, v200
	ds_read_b64_tr_b16 v[136:137], v141 offset:18432
	ds_read_b64_tr_b16 v[138:139], v141 offset:19584
	v_cndmask_b32_e64 v67, 0, v48, s[16:17]
	v_exp_f32_e32 v48, v52
	v_add_f32_e32 v140, v184, v185
	v_add_f32_e32 v152, v152, v140
	v_cndmask_b32_e64 v68, 0, v48, s[18:19]
	v_exp_f32_e32 v48, v53
	v_mfma_f32_32x32x16_bf16 v[80:95], v[100:103], v[144:147], v[80:95]
	v_cndmask_b32_e64 v69, 0, v48, s[20:21]
	v_exp_f32_e32 v48, v54
	s_nop 0
	v_cndmask_b32_e64 v70, 0, v48, s[22:23]
	v_exp_f32_e32 v48, v55
	s_nop 6
	v_exp_f32_e32 v49, v81
	v_exp_f32_e32 v50, v82
	v_exp_f32_e32 v51, v83
	v_cndmask_b32_e64 v71, 0, v48, s[24:25]
	v_exp_f32_e32 v48, v56
	v_exp_f32_e32 v56, v88
	v_exp_f32_e32 v52, v84
	v_exp_f32_e32 v53, v85
	v_cndmask_b32_e64 v72, 0, v48, s[26:27]
	v_exp_f32_e32 v48, v57
	v_exp_f32_e32 v57, v89
	v_exp_f32_e32 v54, v86
	v_exp_f32_e32 v55, v87
	v_cndmask_b32_e64 v73, 0, v48, s[28:29]
	v_exp_f32_e32 v48, v58
	v_exp_f32_e32 v58, v90
	v_cvt_pk_bf16_f32 v88, v72, v73
	v_cndmask_b32_e64 v49, 0, v49, s[48:49]
	v_cndmask_b32_e64 v74, 0, v48, s[30:31]
	v_exp_f32_e32 v48, v59
	v_exp_f32_e32 v59, v91
	v_cndmask_b32_e64 v50, 0, v50, s[50:51]
	v_cndmask_b32_e64 v51, 0, v51, s[52:53]
	v_cndmask_b32_e64 v75, 0, v48, s[34:35]
	v_exp_f32_e32 v48, v60
	v_exp_f32_e32 v60, v92
	v_cvt_pk_bf16_f32 v92, v64, v65
	v_cvt_pk_bf16_f32 v89, v74, v75
	v_cndmask_b32_e64 v76, 0, v48, s[36:37]
	v_exp_f32_e32 v48, v61
	v_exp_f32_e32 v61, v93
	v_cvt_pk_bf16_f32 v93, v66, v67
	v_cndmask_b32_e64 v52, 0, v52, s[54:55]
	v_cndmask_b32_e64 v77, 0, v48, s[38:39]
	v_exp_f32_e32 v48, v62
	v_exp_f32_e32 v62, v94
	v_cvt_pk_bf16_f32 v94, v68, v69
	v_cvt_pk_bf16_f32 v90, v76, v77
	v_cndmask_b32_e64 v78, 0, v48, s[40:41]
	v_exp_f32_e32 v48, v63
	v_exp_f32_e32 v63, v95
	v_cvt_pk_bf16_f32 v95, v70, v71
	v_cndmask_b32_e64 v53, 0, v53, s[56:57]
	v_cndmask_b32_e64 v79, 0, v48, s[42:43]
	s_waitcnt lgkmcnt(0)
; #define MFMA32(a, b, c) __builtin_amdgcn_mfma_f32_32x32x16_bf16((a), (b), (c), 0, 0, 0)
; DI unsigned pk_bf16(float lo, float hi) { f32x2 v = {lo, hi}; bf2_t b = __builtin_convertvector(v, bf2_t); return __builtin_bit_cast(unsigned, b); }
; DI float bf_lo(unsigned u) { return __uint_as_float(u << 16); }
; DI float bf_hi(unsigned u) { return __uint_as_float(u & 0xffff0000u); }
; DI int crow(int i, int h) { return (i & 3) + 8 * (i >> 2) + 4 * h; }
; DI float fast_exp2(float x) { return __builtin_amdgcn_exp2f(x); }
; DI float fast_log2(float x) { return __builtin_amdgcn_logf(x); }
; template <int DQK, bool SB, bool SMAX>
; DI void attn_item(const Params& p, char* smem, int bh, int qb, float Mb) {
;     ...
;           for (int i2 = 0; i2 < 8; ++i2) {
;             float lk[2];
; #pragma unroll
;             for (int e = 0; e < 2; ++e) {
;               const int i = 2 * i2 + e;
;               const float z = fminf(st[kb][i], 100.f);
;               const int key = kb0 + kb * 32 + crow(i, h);
;               const bool valid = !diag || (key < query);
;               float l = -fast_log2(1.f + fast_exp2(z));
;               l = valid ? l : 0.f;
;               lk[e] = l;
;               tsum += l;
;               ca[kb][i] = z + carry;
;             }
;             const unsigned hp = pk_bf16(lk[0], lk[1]);
;             const unsigned lp = pk_bf16(lk[0] - bf_lo(hp), lk[1] - bf_hi(hp));
;             const int kk = kb * 2 + (i2 >> 2), w = i2 & 3;
;             hi[kk][2 * w] = (short)(hp & 0xffffu); hi[kk][2 * w + 1] = (short)(hp >> 16);
;             lo[kk][2 * w] = (short)(lp & 0xffffu); lo[kk][2 * w + 1] = (short)(lp >> 16);
;           }
;     ...
; #pragma unroll
;       for (int kk = 0; kk < 4; ++kk)
; #pragma unroll
;         for (int db = 0; db < 2; ++db) {
;           const s16x4 v0 = __builtin_amdgcn_ds_read_tr16_b64_v4i16((lds_s16x4*)(vc + voff + (16 * kk) * VSTR + 32 * db));
;           const s16x4 v1 = __builtin_amdgcn_ds_read_tr16_b64_v4i16((lds_s16x4*)(vc + voff + (16 * kk + 8) * VSTR + 32 * db));
;           const bf16x8 vf = __builtin_shufflevector(v0, v1, 0, 1, 2, 3, 4, 5, 6, 7);
;           O[db] = MFMA32(vf, pk[kk], O[db]);
;         }
	v_mfma_f32_32x32x16_bf16 v[32:47], v[136:139], v[92:95], v[32:47]
	ds_read_b64_tr_b16 v[136:137], v141 offset:18496
	ds_read_b64_tr_b16 v[138:139], v141 offset:19648
	v_cvt_pk_bf16_f32 v91, v78, v79
	v_exp_f32_e32 v48, v80
	v_cndmask_b32_e64 v54, 0, v54, s[58:59]
	v_cndmask_b32_e64 v55, 0, v55, s[60:61]
	v_cvt_pk_bf16_f32 v85, v50, v51
	v_cndmask_b32_e64 v48, 0, v48, s[46:47]
	s_waitcnt lgkmcnt(0)
	v_mfma_f32_32x32x16_bf16 v[16:31], v[136:139], v[92:95], v[16:31]
	ds_read_b64_tr_b16 v[92:93], v141 offset:20736
	ds_read_b64_tr_b16 v[94:95], v141 offset:21888
	v_cvt_pk_bf16_f32 v84, v48, v49
	v_cvt_pk_bf16_f32 v86, v52, v53
	v_cvt_pk_bf16_f32 v87, v54, v55
	v_cndmask_b32_e64 v56, 0, v56, s[62:63]
	v_cndmask_b32_e64 v57, 0, v57, s[64:65]
	v_cndmask_b32_e64 v58, 0, v58, s[66:67]
	s_waitcnt lgkmcnt(0)
	v_mfma_f32_32x32x16_bf16 v[32:47], v[92:95], v[88:91], v[32:47]
	ds_read_b64_tr_b16 v[92:93], v141 offset:20800
	ds_read_b64_tr_b16 v[94:95], v141 offset:21952
	v_cndmask_b32_e64 v59, 0, v59, s[68:69]
	v_cndmask_b32_e64 v60, 0, v60, s[70:71]
	v_cndmask_b32_e64 v61, 0, v61, s[72:73]
	v_cndmask_b32_e64 v62, 0, v62, s[74:75]
	v_cndmask_b32_e64 v63, 0, v63, s[44:45]
	v_cvt_pk_bf16_f32 v80, v56, v57
	s_waitcnt lgkmcnt(0)
	v_mfma_f32_32x32x16_bf16 v[16:31], v[92:95], v[88:91], v[16:31]
	ds_read_b64_tr_b16 v[88:89], v141 offset:23040
	ds_read_b64_tr_b16 v[90:91], v141 offset:24192
	v_cvt_pk_bf16_f32 v81, v58, v59
	v_cvt_pk_bf16_f32 v82, v60, v61
	v_cvt_pk_bf16_f32 v83, v62, v63
	s_waitcnt lgkmcnt(0)
	v_mfma_f32_32x32x16_bf16 v[32:47], v[88:91], v[84:87], v[32:47]
	ds_read_b64_tr_b16 v[88:89], v141 offset:23104
	ds_read_b64_tr_b16 v[90:91], v141 offset:24256
	s_waitcnt lgkmcnt(0)
	v_mfma_f32_32x32x16_bf16 v[16:31], v[88:91], v[84:87], v[16:31]
	ds_read_b64_tr_b16 v[84:85], v141 offset:25344
	ds_read_b64_tr_b16 v[86:87], v141 offset:26496
	s_waitcnt lgkmcnt(0)
	v_mfma_f32_32x32x16_bf16 v[32:47], v[84:87], v[80:83], v[32:47]
	ds_read_b64_tr_b16 v[84:85], v141 offset:25408
	ds_read_b64_tr_b16 v[86:87], v141 offset:26560
	s_waitcnt lgkmcnt(0)
	v_mfma_f32_32x32x16_bf16 v[16:31], v[84:87], v[80:83], v[16:31]
	s_branch .LBB0_437
.Lsbf_1:
	s_nop 0
	v_add_u32_e32 v143, s78, v197
	v_min_f32_e32 v84, 0x42c80000, v64
	s_nop 0
	v_exp_f32_e32 v64, v84
	v_min_f32_e32 v85, 0x42c80000, v65
	s_nop 0
	s_nop 0
	v_exp_f32_e32 v65, v85
	v_add_f32_e32 v64, 1.0, v64
	v_log_f32_e32 v64, v64
	s_nop 0
	v_add_f32_e32 v65, 1.0, v65
	v_log_f32_e32 v65, v65
	s_nop 0
	s_nop 0
	s_nop 0
	s_nop 0
	v_xor_b32_e32 v64, 0x80000000, v64
	v_add_f32_e32 v80, 0, v64
	v_xor_b32_e32 v65, 0x80000000, v65
	v_add_f32_e32 v81, v65, v80
	v_cvt_pk_bf16_f32 v80, v64, v65
	v_lshlrev_b32_e32 v82, 16, v80
	v_sub_f32_e32 v64, v64, v82
	v_and_b32_e32 v82, 0xffff0000, v80
	v_sub_f32_e32 v65, v65, v82
	v_cvt_pk_bf16_f32 v64, v64, v65
	s_nop 0
	v_min_f32_e32 v86, 0x42c80000, v66
	s_nop 0
	s_nop 0
	s_nop 0
	v_min_f32_e32 v87, 0x42c80000, v67
	s_nop 0
	s_nop 0
	v_exp_f32_e32 v65, v86
	s_nop 0
	v_exp_f32_e32 v67, v87
	s_nop 0
	v_add_f32_e32 v65, 1.0, v65
	v_log_f32_e32 v65, v65
	v_add_f32_e32 v67, 1.0, v67
	v_log_f32_e32 v67, v67
	s_nop 0
	v_xor_b32_e32 v65, 0x80000000, v65
	v_add_f32_e32 v66, v65, v81
	v_xor_b32_e32 v67, 0x80000000, v67
	v_cvt_pk_bf16_f32 v81, v65, v67
	v_lshlrev_b32_e32 v82, 16, v81
	v_sub_f32_e32 v65, v65, v82
	v_and_b32_e32 v82, 0xffff0000, v81
	v_add_f32_e32 v66, v67, v66
	v_sub_f32_e32 v67, v67, v82
	v_cvt_pk_bf16_f32 v65, v65, v67
	s_nop 0
	v_min_f32_e32 v88, 0x42c80000, v68
	s_nop 0
	s_nop 0
	s_nop 0
	v_min_f32_e32 v89, 0x42c80000, v69
	s_nop 0
	s_nop 0
	v_exp_f32_e32 v67, v88
	s_nop 0
	v_exp_f32_e32 v68, v89
	s_nop 0
	v_add_f32_e32 v67, 1.0, v67
	v_log_f32_e32 v67, v67
	v_add_f32_e32 v68, 1.0, v68
	v_log_f32_e32 v68, v68
	s_nop 0
	v_xor_b32_e32 v67, 0x80000000, v67
	v_add_f32_e32 v66, v67, v66
	v_xor_b32_e32 v68, 0x80000000, v68
	v_cvt_pk_bf16_f32 v82, v67, v68
	v_add_f32_e32 v69, v68, v66
	v_lshlrev_b32_e32 v66, 16, v82
	v_sub_f32_e32 v66, v67, v66
	v_and_b32_e32 v67, 0xffff0000, v82
	v_sub_f32_e32 v67, v68, v67
	v_cvt_pk_bf16_f32 v66, v66, v67
	s_nop 0
	v_min_f32_e32 v90, 0x42c80000, v70
	s_nop 0
	s_nop 0
	v_exp_f32_e32 v67, v90
	s_nop 0
	v_min_f32_e32 v156, 0x42c80000, v48
	v_min_f32_e32 v157, 0x42c80000, v49
	v_add_f32_e32 v67, 1.0, v67
	v_log_f32_e32 v67, v67
	s_nop 0
	v_exp_f32_e32 v48, v156
	s_mov_b32 s97, s96
	v_xor_b32_e32 v67, 0x80000000, v67
	v_add_f32_e32 v68, v67, v69
	s_nop 0
	v_min_f32_e32 v91, 0x42c80000, v71
	s_nop 0
	s_nop 0
	v_exp_f32_e32 v69, v91
	s_nop 0
	v_add_f32_e32 v48, 1.0, v48
	v_log_f32_e32 v48, v48
	v_add_f32_e32 v69, 1.0, v69
	v_log_f32_e32 v69, v69
	s_mov_b32 s98, s96
	s_mov_b32 s99, s96
	v_xor_b32_e32 v69, 0x80000000, v69
	v_cvt_pk_bf16_f32 v83, v67, v69
	v_lshlrev_b32_e32 v70, 16, v83
	v_sub_f32_e32 v67, v67, v70
	v_and_b32_e32 v70, 0xffff0000, v83
	v_add_f32_e32 v68, v69, v68
	v_sub_f32_e32 v69, v69, v70
	v_cvt_pk_bf16_f32 v67, v67, v69
	s_nop 0
	v_min_f32_e32 v92, 0x42c80000, v72
	s_nop 0
	s_nop 0
	s_nop 0
	v_min_f32_e32 v93, 0x42c80000, v73
	s_nop 0
	s_nop 0
	v_exp_f32_e32 v69, v92
	s_nop 0
	v_exp_f32_e32 v70, v93
	s_nop 0
	v_add_f32_e32 v69, 1.0, v69
	v_log_f32_e32 v69, v69
	v_add_f32_e32 v70, 1.0, v70
	v_log_f32_e32 v70, v70
	v_xor_b32_e32 v69, 0x80000000, v69
	v_add_f32_e32 v68, v69, v68
	v_xor_b32_e32 v70, 0x80000000, v70
	v_cvt_pk_bf16_f32 v72, v69, v70
	v_add_f32_e32 v71, v70, v68
	v_lshlrev_b32_e32 v68, 16, v72
	v_sub_f32_e32 v68, v69, v68
	v_and_b32_e32 v69, 0xffff0000, v72
	v_sub_f32_e32 v69, v70, v69
	v_cvt_pk_bf16_f32 v68, v68, v69
	s_nop 0
	v_min_f32_e32 v94, 0x42c80000, v74
	s_nop 0
	s_nop 0
	v_exp_f32_e32 v69, v94
	s_nop 0
; DI unsigned pk_bf16(float lo, float hi) { f32x2 v = {lo, hi}; bf2_t b = __builtin_convertvector(v, bf2_t); return __builtin_bit_cast(unsigned, b); }
; DI float bf_lo(unsigned u) { return __uint_as_float(u << 16); }
; DI float bf_hi(unsigned u) { return __uint_as_float(u & 0xffff0000u); }
; DI int crow(int i, int h) { return (i & 3) + 8 * (i >> 2) + 4 * h; }
; DI float fast_exp2(float x) { return __builtin_amdgcn_exp2f(x); }
; DI float fast_log2(float x) { return __builtin_amdgcn_logf(x); }
; template <int DQK, bool SB, bool SMAX>
; DI void attn_item(const Params& p, char* smem, int bh, int qb, float Mb) {
;     ...
;           for (int i2 = 0; i2 < 8; ++i2) {
;             float lk[2];
; #pragma unroll
;             for (int e = 0; e < 2; ++e) {
;               const int i = 2 * i2 + e;
;               const float z = fminf(st[kb][i], 100.f);
;               const int key = kb0 + kb * 32 + crow(i, h);
;               const bool valid = !diag || (key < query);
;               float l = -fast_log2(1.f + fast_exp2(z));
;               l = valid ? l : 0.f;
;               lk[e] = l;
;               tsum += l;
;               ca[kb][i] = z + carry;
;             }
;             const unsigned hp = pk_bf16(lk[0], lk[1]);
;             const unsigned lp = pk_bf16(lk[0] - bf_lo(hp), lk[1] - bf_hi(hp));
;             const int kk = kb * 2 + (i2 >> 2), w = i2 & 3;
;             hi[kk][2 * w] = (short)(hp & 0xffffu); hi[kk][2 * w + 1] = (short)(hp >> 16);
;             lo[kk][2 * w] = (short)(lp & 0xffffu); lo[kk][2 * w + 1] = (short)(lp >> 16);
;           }
	v_add_f32_e32 v69, 1.0, v69
	v_log_f32_e32 v69, v69
	s_nop 0
	v_xor_b32_e32 v69, 0x80000000, v69
	v_add_f32_e32 v70, v69, v71
	s_nop 0
	v_min_f32_e32 v95, 0x42c80000, v75
	s_nop 0
	s_nop 0
	v_exp_f32_e32 v71, v95
	s_nop 0
	v_add_f32_e32 v71, 1.0, v71
	v_log_f32_e32 v71, v71
	s_nop 0
	v_xor_b32_e32 v71, 0x80000000, v71
	v_cvt_pk_bf16_f32 v73, v69, v71
	v_lshlrev_b32_e32 v74, 16, v73
	v_sub_f32_e32 v69, v69, v74
	v_and_b32_e32 v74, 0xffff0000, v73
	v_add_f32_e32 v70, v71, v70
	v_sub_f32_e32 v71, v71, v74
	v_cvt_pk_bf16_f32 v69, v69, v71
	s_nop 0
	v_min_f32_e32 v154, 0x42c80000, v76
	s_nop 0
	s_nop 0
	s_nop 0
	v_min_f32_e32 v155, 0x42c80000, v77
	s_nop 0
	s_nop 0
	v_exp_f32_e32 v71, v154
	s_nop 0
	v_exp_f32_e32 v74, v155
	s_nop 0
	v_add_f32_e32 v71, 1.0, v71
	v_log_f32_e32 v71, v71
	v_add_f32_e32 v74, 1.0, v74
	v_log_f32_e32 v74, v74
	v_xor_b32_e32 v71, 0x80000000, v71
	v_add_f32_e32 v70, v71, v70
	v_xor_b32_e32 v75, 0x80000000, v74
	v_cvt_pk_bf16_f32 v74, v71, v75
	v_add_f32_e32 v76, v75, v70
	v_lshlrev_b32_e32 v70, 16, v74
	v_sub_f32_e32 v70, v71, v70
	v_and_b32_e32 v71, 0xffff0000, v74
	v_sub_f32_e32 v71, v75, v71
	v_cvt_pk_bf16_f32 v70, v70, v71
	s_nop 0
	v_min_f32_e32 v158, 0x42c80000, v78
	s_nop 0
	s_nop 0
	v_exp_f32_e32 v71, v158
	s_nop 0
	v_add_f32_e32 v71, 1.0, v71
	v_log_f32_e32 v71, v71
	s_nop 0
	v_xor_b32_e32 v71, 0x80000000, v71
	v_add_f32_e32 v75, v71, v76
	s_nop 0
	v_min_f32_e32 v159, 0x42c80000, v79
	s_nop 0
	s_nop 0
	v_exp_f32_e32 v76, v159
	s_nop 0
	v_add_f32_e32 v76, 1.0, v76
	v_log_f32_e32 v76, v76
	s_nop 0
	v_xor_b32_e32 v76, 0x80000000, v76
	v_add_f32_e32 v77, v76, v75
	v_cvt_pk_bf16_f32 v75, v71, v76
	v_lshlrev_b32_e32 v78, 16, v75
	v_sub_f32_e32 v71, v71, v78
	v_and_b32_e32 v78, 0xffff0000, v75
	v_sub_f32_e32 v76, v76, v78
	v_cvt_pk_bf16_f32 v71, v71, v76
	s_nop 0
	s_nop 0
	s_nop 0
	s_nop 0
	v_exp_f32_e32 v49, v157
	s_nop 0
	v_xor_b32_e32 v48, 0x80000000, v48
	v_add_f32_e32 v76, v48, v77
	v_add_f32_e32 v49, 1.0, v49
	v_log_f32_e32 v49, v49
	s_nop 0
	v_xor_b32_e32 v49, 0x80000000, v49
	v_cvt_pk_bf16_f32 v136, v48, v49
	v_add_f32_e32 v77, v49, v76
	v_lshlrev_b32_e32 v76, 16, v136
	v_sub_f32_e32 v48, v48, v76
	v_and_b32_e32 v76, 0xffff0000, v136
	v_sub_f32_e32 v49, v49, v76
	v_cvt_pk_bf16_f32 v76, v48, v49
	s_nop 0
	v_min_f32_e32 v160, 0x42c80000, v50
	s_nop 0
	s_nop 0
	s_nop 0
	v_min_f32_e32 v161, 0x42c80000, v51
	s_nop 0
	s_nop 0
	v_exp_f32_e32 v48, v160
	s_nop 0
	v_exp_f32_e32 v50, v161
	s_nop 0
	v_add_f32_e32 v48, 1.0, v48
	v_log_f32_e32 v48, v48
	v_add_f32_e32 v50, 1.0, v50
	v_log_f32_e32 v50, v50
	v_xor_b32_e32 v48, 0x80000000, v48
	v_add_f32_e32 v49, v48, v77
	v_xor_b32_e32 v50, 0x80000000, v50
	v_cvt_pk_bf16_f32 v137, v48, v50
	v_lshlrev_b32_e32 v51, 16, v137
	v_sub_f32_e32 v48, v48, v51
	v_and_b32_e32 v51, 0xffff0000, v137
	v_add_f32_e32 v49, v50, v49
	v_sub_f32_e32 v50, v50, v51
	v_cvt_pk_bf16_f32 v77, v48, v50
	s_nop 0
	v_min_f32_e32 v162, 0x42c80000, v52
	s_nop 0
	s_nop 0
	s_nop 0
	v_min_f32_e32 v163, 0x42c80000, v53
	s_nop 0
	s_nop 0
	v_exp_f32_e32 v48, v162
	s_nop 0
	v_exp_f32_e32 v50, v163
	s_nop 0
	v_add_f32_e32 v48, 1.0, v48
	v_log_f32_e32 v48, v48
	v_add_f32_e32 v50, 1.0, v50
	v_log_f32_e32 v50, v50
	v_pk_add_f32 v[52:53], v[152:153], v[88:89] op_sel_hi:[0,1]
	v_xor_b32_e32 v48, 0x80000000, v48
	v_add_f32_e32 v49, v48, v49
	v_xor_b32_e32 v50, 0x80000000, v50
	v_cvt_pk_bf16_f32 v138, v48, v50
	v_lshlrev_b32_e32 v51, 16, v138
	v_sub_f32_e32 v48, v48, v51
	v_and_b32_e32 v51, 0xffff0000, v138
	v_add_f32_e32 v49, v50, v49
	v_sub_f32_e32 v50, v50, v51
	v_cvt_pk_bf16_f32 v78, v48, v50
	s_nop 0
	v_min_f32_e32 v164, 0x42c80000, v54
	s_nop 0
	s_nop 0
	s_nop 0
	v_min_f32_e32 v165, 0x42c80000, v55
	s_nop 0
	s_nop 0
	v_exp_f32_e32 v48, v164
	s_nop 0
	v_exp_f32_e32 v50, v165
	s_nop 0
	v_add_f32_e32 v48, 1.0, v48
	v_log_f32_e32 v48, v48
	v_add_f32_e32 v50, 1.0, v50
	v_log_f32_e32 v50, v50
	v_pk_add_f32 v[54:55], v[152:153], v[90:91] op_sel_hi:[0,1]
	v_xor_b32_e32 v48, 0x80000000, v48
	v_add_f32_e32 v49, v48, v49
	v_xor_b32_e32 v50, 0x80000000, v50
	v_cvt_pk_bf16_f32 v139, v48, v50
	v_lshlrev_b32_e32 v51, 16, v139
	v_sub_f32_e32 v48, v48, v51
	v_and_b32_e32 v51, 0xffff0000, v139
	v_add_f32_e32 v49, v50, v49
	v_sub_f32_e32 v50, v50, v51
	v_cvt_pk_bf16_f32 v79, v48, v50
	s_nop 0
	v_min_f32_e32 v166, 0x42c80000, v56
	s_nop 0
	s_nop 0
	s_nop 0
	v_min_f32_e32 v167, 0x42c80000, v57
	s_nop 0
	s_nop 0
	v_exp_f32_e32 v48, v166
	s_nop 0
	v_exp_f32_e32 v50, v167
	s_nop 0
	v_add_f32_e32 v48, 1.0, v48
	v_log_f32_e32 v48, v48
	v_add_f32_e32 v50, 1.0, v50
	v_log_f32_e32 v50, v50
	v_pk_add_f32 v[56:57], v[152:153], v[92:93] op_sel_hi:[0,1]
	v_xor_b32_e32 v48, 0x80000000, v48
	v_add_f32_e32 v49, v48, v49
	v_xor_b32_e32 v50, 0x80000000, v50
	v_cvt_pk_bf16_f32 v140, v48, v50
	v_lshlrev_b32_e32 v51, 16, v140
	v_sub_f32_e32 v48, v48, v51
	v_and_b32_e32 v51, 0xffff0000, v140
	v_add_f32_e32 v49, v50, v49
	v_sub_f32_e32 v50, v50, v51
	v_cvt_pk_bf16_f32 v144, v48, v50
	s_nop 0
	v_min_f32_e32 v168, 0x42c80000, v58
	s_nop 0
	s_nop 0
	s_nop 0
	v_min_f32_e32 v169, 0x42c80000, v59
	s_nop 0
	s_nop 0
	v_exp_f32_e32 v48, v168
	s_nop 0
	v_exp_f32_e32 v50, v169
	s_nop 0
	v_add_f32_e32 v48, 1.0, v48
	v_log_f32_e32 v48, v48
	v_add_f32_e32 v50, 1.0, v50
	v_log_f32_e32 v50, v50
	v_pk_add_f32 v[58:59], v[152:153], v[94:95] op_sel_hi:[0,1]
	v_xor_b32_e32 v48, 0x80000000, v48
	v_add_f32_e32 v49, v48, v49
	v_xor_b32_e32 v50, 0x80000000, v50
	v_cvt_pk_bf16_f32 v141, v48, v50
	v_lshlrev_b32_e32 v51, 16, v141
	v_sub_f32_e32 v48, v48, v51
	v_and_b32_e32 v51, 0xffff0000, v141
	v_add_f32_e32 v49, v50, v49
	v_sub_f32_e32 v50, v50, v51
	v_cvt_pk_bf16_f32 v145, v48, v50
; #define MFMA32(a, b, c) __builtin_amdgcn_mfma_f32_32x32x16_bf16((a), (b), (c), 0, 0, 0)
; DI unsigned pk_bf16(float lo, float hi) { f32x2 v = {lo, hi}; bf2_t b = __builtin_convertvector(v, bf2_t); return __builtin_bit_cast(unsigned, b); }
; DI int crow(int i, int h) { return (i & 3) + 8 * (i >> 2) + 4 * h; }
; DI float fast_exp2(float x) { return __builtin_amdgcn_exp2f(x); }
; template <int DQK, bool SB, bool SMAX>
; DI void attn_item(const Params& p, char* smem, int bh, int qb, float Mb) {
;     ...
;         tsum += other_half(tsum);
; #pragma unroll
;         for (int s = 0; s < 2; ++s) {
;           ca[0] = MFMA32(tri[s], hi[s], ca[0]);
;           ca[0] = MFMA32(tri[s], lo[s], ca[0]);
;           ca[0] = MFMA32(ones, hi[2 + s], ca[0]);
;           ca[0] = MFMA32(ones, lo[2 + s], ca[0]);
;           ca[1] = MFMA32(tri[s], hi[2 + s], ca[1]);
;           ca[1] = MFMA32(tri[s], lo[2 + s], ca[1]);
;         }
; #pragma unroll
;         for (int kb = 0; kb < 2; ++kb)
; #pragma unroll
;           for (int i = 0; i < 16; ++i) {
;             const int key = kb0 + kb * 32 + crow(i, h);
;             const bool valid = !diag || (key < query);
;             st[kb][i] = valid ? fast_exp2(ca[kb][i]) : 0.f;
;           }
;         carry += tsum;
;     ...
; #pragma unroll
;           for (int e = 0; e < 4; ++e) w[e] = pk_bf16(st[kb][8 * s + 2 * e], st[kb][8 * s + 2 * e + 1]);
;           pk[kb * 2 + s] = __builtin_bit_cast(bf16x8, w);
;         }
; #pragma unroll
;       for (int kk = 0; kk < 4; ++kk)
; #pragma unroll
;         for (int db = 0; db < 2; ++db) {
;           const s16x4 v0 = __builtin_amdgcn_ds_read_tr16_b64_v4i16((lds_s16x4*)(vc + voff + (16 * kk) * VSTR + 32 * db));
;           const s16x4 v1 = __builtin_amdgcn_ds_read_tr16_b64_v4i16((lds_s16x4*)(vc + voff + (16 * kk + 8) * VSTR + 32 * db));
;           const bf16x8 vf = __builtin_shufflevector(v0, v1, 0, 1, 2, 3, 4, 5, 6, 7);
;           O[db] = MFMA32(vf, pk[kk], O[db]);
	s_nop 0
	v_min_f32_e32 v170, 0x42c80000, v60
	s_nop 0
	s_nop 0
	s_nop 0
	v_min_f32_e32 v171, 0x42c80000, v61
	s_nop 0
	s_nop 0
	v_exp_f32_e32 v48, v170
	s_nop 0
	v_exp_f32_e32 v50, v171
	s_nop 0
	v_add_f32_e32 v48, 1.0, v48
	v_log_f32_e32 v48, v48
	v_add_f32_e32 v50, 1.0, v50
	v_log_f32_e32 v50, v50
	v_pk_add_f32 v[60:61], v[152:153], v[154:155] op_sel_hi:[0,1]
	v_xor_b32_e32 v48, 0x80000000, v48
	v_add_f32_e32 v49, v48, v49
	v_xor_b32_e32 v50, 0x80000000, v50
	v_cvt_pk_bf16_f32 v142, v48, v50
	v_lshlrev_b32_e32 v51, 16, v142
	v_sub_f32_e32 v48, v48, v51
	v_and_b32_e32 v51, 0xffff0000, v142
	v_add_f32_e32 v49, v50, v49
	v_sub_f32_e32 v50, v50, v51
	v_cvt_pk_bf16_f32 v146, v48, v50
	s_nop 0
	v_min_f32_e32 v182, 0x42c80000, v62
	s_nop 0
	s_nop 0
	s_nop 0
	v_min_f32_e32 v183, 0x42c80000, v63
	s_nop 0
	s_nop 0
	v_exp_f32_e32 v48, v182
	s_nop 0
	v_exp_f32_e32 v50, v183
	s_nop 0
	v_add_f32_e32 v48, 1.0, v48
	v_log_f32_e32 v48, v48
	v_add_f32_e32 v50, 1.0, v50
	v_log_f32_e32 v50, v50
	v_pk_add_f32 v[62:63], v[152:153], v[158:159] op_sel_hi:[0,1]
	v_xor_b32_e32 v48, 0x80000000, v48
	v_add_f32_e32 v49, v48, v49
	v_xor_b32_e32 v50, 0x80000000, v50
	v_cvt_pk_bf16_f32 v143, v48, v50
	v_add_f32_e32 v184, v50, v49
	v_lshlrev_b32_e32 v49, 16, v143
	v_sub_f32_e32 v48, v48, v49
	v_and_b32_e32 v49, 0xffff0000, v143
	v_sub_f32_e32 v49, v50, v49
	v_cvt_pk_bf16_f32 v147, v48, v49
	v_mov_b32_e32 v48, v184
	v_mov_b32_e32 v49, v184
	s_nop 1
	v_permlane32_swap_b32_e32 v48, v49
	v_cndmask_b32_e64 v185, v48, v49, s[8:9]
	v_pk_add_f32 v[50:51], v[152:153], v[86:87] op_sel_hi:[0,1]
	v_pk_add_f32 v[48:49], v[152:153], v[84:85] op_sel_hi:[0,1]
	v_pk_add_f32 v[94:95], v[152:153], v[182:183] op_sel_hi:[0,1]
	v_pk_add_f32 v[92:93], v[152:153], v[170:171] op_sel_hi:[0,1]
	v_mfma_f32_32x32x16_bf16 v[48:63], v[96:99], v[80:83], v[48:63]
	v_add_f32_e64 v90, v152, v168
	v_add_f32_e64 v91, v152, v169
	v_add_f32_e64 v88, v152, v166
	v_add_f32_e64 v89, v152, v167
	v_add_f32_e64 v86, v152, v164
	v_add_f32_e64 v87, v152, v165
	v_pk_add_f32 v[84:85], v[152:153], v[162:163] op_sel_hi:[0,1]
	v_pk_add_f32 v[82:83], v[152:153], v[160:161] op_sel_hi:[0,1]
	v_pk_add_f32 v[80:81], v[152:153], v[156:157] op_sel_hi:[0,1]
	v_mfma_f32_32x32x16_bf16 v[48:63], v[96:99], v[64:67], v[48:63]
	v_mov_b64_e32 v[64:65], s[96:97]
	v_mov_b64_e32 v[66:67], s[98:99]
	s_nop 1
	v_mfma_f32_32x32x16_bf16 v[48:63], v[64:67], v[136:139], v[48:63]
	v_mfma_f32_32x32x16_bf16 v[48:63], v[64:67], v[76:79], v[48:63]
	v_mfma_f32_32x32x16_bf16 v[48:63], v[100:103], v[72:75], v[48:63]
	v_mfma_f32_32x32x16_bf16 v[48:63], v[100:103], v[68:71], v[48:63]
	v_mfma_f32_32x32x16_bf16 v[48:63], v[64:67], v[140:143], v[48:63]
	v_mfma_f32_32x32x16_bf16 v[48:63], v[64:67], v[144:147], v[48:63]
	v_mfma_f32_32x32x16_bf16 v[80:95], v[96:99], v[136:139], v[80:95]
	s_nop 10
	v_exp_f32_e32 v64, v48
	s_nop 0
	s_nop 0
	v_exp_f32_e32 v65, v49
	v_mfma_f32_32x32x16_bf16 v[80:95], v[96:99], v[76:79], v[80:95]
	s_nop 0
	v_exp_f32_e32 v66, v50
	s_nop 0
	s_nop 0
	v_exp_f32_e32 v67, v51
	v_mfma_f32_32x32x16_bf16 v[80:95], v[100:103], v[140:143], v[80:95]
	v_add_u32_e32 v141, v198, v200
	ds_read_b64_tr_b16 v[136:137], v141 offset:18432
	ds_read_b64_tr_b16 v[138:139], v141 offset:19584
	s_nop 0
	v_exp_f32_e32 v68, v52
	v_add_f32_e32 v140, v184, v185
	v_add_f32_e32 v152, v152, v140
	s_nop 0
	v_exp_f32_e32 v69, v53
	v_mfma_f32_32x32x16_bf16 v[80:95], v[100:103], v[144:147], v[80:95]
	s_nop 0
	v_exp_f32_e32 v70, v54
	s_nop 0
	s_nop 0
	v_exp_f32_e32 v71, v55
	s_nop 6
	v_exp_f32_e32 v49, v81
	v_exp_f32_e32 v50, v82
	v_exp_f32_e32 v51, v83
	s_nop 0
	v_exp_f32_e32 v72, v56
	v_exp_f32_e32 v56, v88
	v_exp_f32_e32 v52, v84
	v_exp_f32_e32 v53, v85
	s_nop 0
	v_exp_f32_e32 v73, v57
	v_exp_f32_e32 v57, v89
	v_exp_f32_e32 v54, v86
	v_exp_f32_e32 v55, v87
	s_nop 0
	v_exp_f32_e32 v74, v58
	v_exp_f32_e32 v58, v90
	v_cvt_pk_bf16_f32 v88, v72, v73
	s_nop 0
	s_nop 0
	v_exp_f32_e32 v75, v59
	v_exp_f32_e32 v59, v91
	s_nop 0
	s_nop 0
	s_nop 0
	v_exp_f32_e32 v76, v60
	v_exp_f32_e32 v60, v92
	v_cvt_pk_bf16_f32 v92, v64, v65
	v_cvt_pk_bf16_f32 v89, v74, v75
	s_nop 0
	v_exp_f32_e32 v77, v61
	v_exp_f32_e32 v61, v93
	v_cvt_pk_bf16_f32 v93, v66, v67
	s_nop 0
	s_nop 0
	v_exp_f32_e32 v78, v62
	v_exp_f32_e32 v62, v94
	v_cvt_pk_bf16_f32 v94, v68, v69
	v_cvt_pk_bf16_f32 v90, v76, v77
	s_nop 0
	v_exp_f32_e32 v79, v63
	v_exp_f32_e32 v63, v95
	v_cvt_pk_bf16_f32 v95, v70, v71
	s_nop 0
	s_nop 0
	s_waitcnt lgkmcnt(0)
	v_mfma_f32_32x32x16_bf16 v[32:47], v[136:139], v[92:95], v[32:47]
	ds_read_b64_tr_b16 v[136:137], v141 offset:18496
	ds_read_b64_tr_b16 v[138:139], v141 offset:19648
	v_cvt_pk_bf16_f32 v91, v78, v79
	v_exp_f32_e32 v48, v80
	s_nop 0
	s_nop 0
	v_cvt_pk_bf16_f32 v85, v50, v51
	s_nop 0
	s_waitcnt lgkmcnt(0)
	v_mfma_f32_32x32x16_bf16 v[16:31], v[136:139], v[92:95], v[16:31]
	ds_read_b64_tr_b16 v[92:93], v141 offset:20736
	ds_read_b64_tr_b16 v[94:95], v141 offset:21888
	v_cvt_pk_bf16_f32 v84, v48, v49
	v_cvt_pk_bf16_f32 v86, v52, v53
	v_cvt_pk_bf16_f32 v87, v54, v55
	s_nop 0
	s_nop 0
	s_nop 0
	s_waitcnt lgkmcnt(0)
	v_mfma_f32_32x32x16_bf16 v[32:47], v[92:95], v[88:91], v[32:47]
	ds_read_b64_tr_b16 v[92:93], v141 offset:20800
	ds_read_b64_tr_b16 v[94:95], v141 offset:21952
	s_nop 0
	s_nop 0
	s_nop 0
	s_nop 0
	s_nop 0
	v_cvt_pk_bf16_f32 v80, v56, v57
	s_waitcnt lgkmcnt(0)
	v_mfma_f32_32x32x16_bf16 v[16:31], v[92:95], v[88:91], v[16:31]
	ds_read_b64_tr_b16 v[88:89], v141 offset:23040
	ds_read_b64_tr_b16 v[90:91], v141 offset:24192
	v_cvt_pk_bf16_f32 v81, v58, v59
	v_cvt_pk_bf16_f32 v82, v60, v61
	v_cvt_pk_bf16_f32 v83, v62, v63
	s_waitcnt lgkmcnt(0)
	v_mfma_f32_32x32x16_bf16 v[32:47], v[88:91], v[84:87], v[32:47]
	ds_read_b64_tr_b16 v[88:89], v141 offset:23104
	ds_read_b64_tr_b16 v[90:91], v141 offset:24256
	s_waitcnt lgkmcnt(0)
	v_mfma_f32_32x32x16_bf16 v[16:31], v[88:91], v[84:87], v[16:31]
	ds_read_b64_tr_b16 v[84:85], v141 offset:25344
	ds_read_b64_tr_b16 v[86:87], v141 offset:26496
	s_waitcnt lgkmcnt(0)
	v_mfma_f32_32x32x16_bf16 v[32:47], v[84:87], v[80:83], v[32:47]
	ds_read_b64_tr_b16 v[84:85], v141 offset:25408
	ds_read_b64_tr_b16 v[86:87], v141 offset:26560
	s_waitcnt lgkmcnt(0)
	v_mfma_f32_32x32x16_bf16 v[16:31], v[84:87], v[80:83], v[16:31]

; DI unsigned pk_bf16(float lo, float hi) { f32x2 v = {lo, hi}; bf2_t b = __builtin_convertvector(v, bf2_t); return __builtin_bit_cast(unsigned, b); }
; DI float bf_lo(unsigned u) { return __uint_as_float(u << 16); }
; DI float bf_hi(unsigned u) { return __uint_as_float(u & 0xffff0000u); }
; DI int crow(int i, int h) { return (i & 3) + 8 * (i >> 2) + 4 * h; }
; DI float fast_exp2(float x) { return __builtin_amdgcn_exp2f(x); }
; DI float fast_log2(float x) { return __builtin_amdgcn_logf(x); }
; #define AT_LOAD(SET, IT) { const int kl_ = AT_KB(IT); \
;     _Pragma("unroll") for (int i = 0; i < KPT; ++i) kreg[SET][i] = *(const u32x4*)(Kg + (size_t)kl_ * DQK + (tid + 256 * i) * 8); \
;     _Pragma("unroll") for (int i = 0; i < 2; ++i) vreg[SET][i] = *(const u32x4*)(Vg + (size_t)kl_ * 64 + (tid + 256 * i) * 8); \
;     __builtin_amdgcn_sched_barrier(0); }
; template <int DQK, bool SB, bool SMAX>
; DI void attn_item(const Params& p, char* smem, int bh, int qb, float Mb) {
;     ...
;     AT_WRITE(0, st2 ^ 1)
;     AT_LOAD(0, (it + 2 < nt) ? it + 2 : nt - 1)
;     if (active) {
;       const bool diag = (kb0 + 64 > qw0);
;       bf16x8 pk[4];
;     ...
;           for (int i2 = 0; i2 < 8; ++i2) {
;             float lk[2];
; #pragma unroll
;             for (int e = 0; e < 2; ++e) {
;               const int i = 2 * i2 + e;
;               const float z = fminf(st[kb][i], 100.f);
;               const int key = kb0 + kb * 32 + crow(i, h);
;               const bool valid = !diag || (key < query);
;               float l = -fast_log2(1.f + fast_exp2(z));
;               l = valid ? l : 0.f;
;               lk[e] = l;
;               tsum += l;
;               ca[kb][i] = z + carry;
;             }
;             const unsigned hp = pk_bf16(lk[0], lk[1]);
;             const unsigned lp = pk_bf16(lk[0] - bf_lo(hp), lk[1] - bf_hi(hp));
;             const int kk = kb * 2 + (i2 >> 2), w = i2 & 3;
;             hi[kk][2 * w] = (short)(hp & 0xffffu); hi[kk][2 * w + 1] = (short)(hp >> 16);
;             lo[kk][2 * w] = (short)(lp & 0xffffu); lo[kk][2 * w + 1] = (short)(lp >> 16);
;           }
.LBB0_442:
	s_or_b64 exec, exec, s[2:3]
	s_add_i32 s2, s4, 1
	s_xor_b32 s3, s4, 0x3fffffe
	s_add_i32 s3, s3, s1
	s_lshl_b32 s3, s3, 6
	s_cmp_lt_u32 s2, s1
	s_cselect_b32 s2, s3, 0
	s_ashr_i32 s3, s2, 31
	s_lshl_b64 s[2:3], s[2:3], 7
	v_lshl_add_u64 v[80:81], v[148:149], 0, s[2:3]
	s_waitcnt vmcnt(3)
	ds_write_b128 v203, v[120:123]
	s_waitcnt vmcnt(2)
	ds_write_b128 v204, v[124:127]
	s_waitcnt vmcnt(1)
	ds_write_b128 v203, v[128:131] offset:18432
	s_waitcnt vmcnt(0)
	ds_write_b128 v204, v[132:135] offset:18432
	v_add_co_u32_e32 v82, vcc, s7, v80
	s_nop 1
	v_addc_co_u32_e32 v83, vcc, 0, v81, vcc
	global_load_dwordx4 v[120:123], v[80:81], off
	global_load_dwordx4 v[124:127], v[82:83], off
	v_lshl_add_u64 v[80:81], v[150:151], 0, s[2:3]
	v_add_co_u32_e32 v82, vcc, 0x1000, v80
	s_nop 1
	v_addc_co_u32_e32 v83, vcc, 0, v81, vcc
	global_load_dwordx4 v[128:131], v[80:81], off
	global_load_dwordx4 v[132:135], v[82:83], off
	s_and_saveexec_b64 s[80:81], s[12:13]
	s_cbranch_execz .LBB0_444
	v_cmp_le_i32_e64 s[44:45], s14, v181
	s_nop 0
	s_cmp_eq_u64 s[44:45], exec
	s_cbranch_scc1 .Lsbf_2
	s_nop 0
	v_add_u32_e32 v143, s78, v197
	v_min_f32_e32 v84, 0x42c80000, v64
	s_nop 0
	v_exp_f32_e32 v64, v84
	v_min_f32_e32 v85, 0x42c80000, v65
	v_add_u32_e32 v65, 0x41, v143
	v_cmp_lt_i32_e64 s[2:3], v65, v176
	v_exp_f32_e32 v65, v85
	v_add_f32_e32 v64, 1.0, v64
	v_log_f32_e32 v64, v64
	v_add_u32_e32 v80, 64, v143
	v_add_f32_e32 v65, 1.0, v65
	v_log_f32_e32 v65, v65
	v_cmp_le_i32_e64 s[44:45], s14, v181
	v_cmp_lt_i32_e32 vcc, v80, v176
	s_or_b64 vcc, s[44:45], vcc
	s_or_b64 s[12:13], s[44:45], s[2:3]
	v_cndmask_b32_e64 v64, 0, -v64, vcc
	v_add_f32_e32 v80, 0, v64
	v_cndmask_b32_e64 v65, 0, -v65, s[12:13]
	v_add_f32_e32 v81, v65, v80
	v_cvt_pk_bf16_f32 v80, v64, v65
	v_lshlrev_b32_e32 v82, 16, v80
	v_sub_f32_e32 v64, v64, v82
	v_and_b32_e32 v82, 0xffff0000, v80
	v_sub_f32_e32 v65, v65, v82
	v_cvt_pk_bf16_f32 v64, v64, v65
	s_nop 0
	v_min_f32_e32 v86, 0x42c80000, v66
	v_add_u32_e32 v65, 0x42, v143
	s_nop 0
	v_cmp_lt_i32_e64 s[2:3], v65, v176
	v_min_f32_e32 v87, 0x42c80000, v67
	v_add_u32_e32 v67, 0x43, v143
	s_or_b64 s[14:15], s[44:45], s[2:3]
	v_exp_f32_e32 v65, v86
	v_cmp_lt_i32_e64 s[2:3], v67, v176
	v_exp_f32_e32 v67, v87
	s_or_b64 s[16:17], s[44:45], s[2:3]
	v_add_f32_e32 v65, 1.0, v65
	v_log_f32_e32 v65, v65
	v_add_f32_e32 v67, 1.0, v67
	v_log_f32_e32 v67, v67
	s_nop 0
	v_cndmask_b32_e64 v65, 0, -v65, s[14:15]
	v_add_f32_e32 v66, v65, v81
	v_cndmask_b32_e64 v67, 0, -v67, s[16:17]
	v_cvt_pk_bf16_f32 v81, v65, v67
	v_lshlrev_b32_e32 v82, 16, v81
	v_sub_f32_e32 v65, v65, v82
	v_and_b32_e32 v82, 0xffff0000, v81
	v_add_f32_e32 v66, v67, v66
	v_sub_f32_e32 v67, v67, v82
	v_cvt_pk_bf16_f32 v65, v65, v67
	s_nop 0
	v_min_f32_e32 v88, 0x42c80000, v68
	v_add_u32_e32 v67, 0x48, v143
	s_nop 0
	v_cmp_lt_i32_e64 s[2:3], v67, v176
	v_min_f32_e32 v89, 0x42c80000, v69
	v_add_u32_e32 v68, 0x49, v143
	s_or_b64 s[18:19], s[44:45], s[2:3]
	v_exp_f32_e32 v67, v88
	v_cmp_lt_i32_e64 s[2:3], v68, v176
	v_exp_f32_e32 v68, v89
	s_or_b64 s[20:21], s[44:45], s[2:3]
	v_add_f32_e32 v67, 1.0, v67
	v_log_f32_e32 v67, v67
	v_add_f32_e32 v68, 1.0, v68
	v_log_f32_e32 v68, v68
	s_nop 0
	v_cndmask_b32_e64 v67, 0, -v67, s[18:19]
	v_add_f32_e32 v66, v67, v66
	v_cndmask_b32_e64 v68, 0, -v68, s[20:21]
	v_cvt_pk_bf16_f32 v82, v67, v68
	v_add_f32_e32 v69, v68, v66
	v_lshlrev_b32_e32 v66, 16, v82
	v_sub_f32_e32 v66, v67, v66
	v_and_b32_e32 v67, 0xffff0000, v82
	v_sub_f32_e32 v67, v68, v67
	v_cvt_pk_bf16_f32 v66, v66, v67
	s_nop 0
	v_min_f32_e32 v90, 0x42c80000, v70
	v_add_u32_e32 v67, 0x4a, v143
	v_cmp_lt_i32_e64 s[2:3], v67, v176
	v_exp_f32_e32 v67, v90
	s_or_b64 s[22:23], s[44:45], s[2:3]
	v_min_f32_e32 v156, 0x42c80000, v48
	v_min_f32_e32 v157, 0x42c80000, v49
	v_add_f32_e32 v67, 1.0, v67
	v_log_f32_e32 v67, v67
	v_add_u32_e32 v49, 0x61, v143
	v_exp_f32_e32 v48, v156
	s_mov_b32 s97, s96
	v_cndmask_b32_e64 v67, 0, -v67, s[22:23]
	v_add_f32_e32 v68, v67, v69
	s_nop 0
	v_min_f32_e32 v91, 0x42c80000, v71
	v_add_u32_e32 v69, 0x4b, v143
	v_cmp_lt_i32_e64 s[2:3], v69, v176
	v_exp_f32_e32 v69, v91
	s_or_b64 s[24:25], s[44:45], s[2:3]
	v_add_f32_e32 v48, 1.0, v48
	v_log_f32_e32 v48, v48
	v_add_f32_e32 v69, 1.0, v69
	v_log_f32_e32 v69, v69
	s_mov_b32 s98, s96
	s_mov_b32 s99, s96
	v_cndmask_b32_e64 v69, 0, -v69, s[24:25]
	v_cvt_pk_bf16_f32 v83, v67, v69
	v_lshlrev_b32_e32 v70, 16, v83
	v_sub_f32_e32 v67, v67, v70
	v_and_b32_e32 v70, 0xffff0000, v83
	v_add_f32_e32 v68, v69, v68
	v_sub_f32_e32 v69, v69, v70
	v_cvt_pk_bf16_f32 v67, v67, v69
	s_nop 0
	v_min_f32_e32 v92, 0x42c80000, v72
	v_add_u32_e32 v69, 0x50, v143
	s_nop 0
	v_cmp_lt_i32_e64 s[2:3], v69, v176
	v_min_f32_e32 v93, 0x42c80000, v73
	v_add_u32_e32 v70, 0x51, v143
	s_or_b64 s[26:27], s[44:45], s[2:3]
	v_exp_f32_e32 v69, v92
	v_cmp_lt_i32_e64 s[2:3], v70, v176
	v_exp_f32_e32 v70, v93
	s_or_b64 s[28:29], s[44:45], s[2:3]
	v_add_f32_e32 v69, 1.0, v69
	v_log_f32_e32 v69, v69
	v_add_f32_e32 v70, 1.0, v70
	v_log_f32_e32 v70, v70
	v_cndmask_b32_e64 v69, 0, -v69, s[26:27]
	v_add_f32_e32 v68, v69, v68
	v_cndmask_b32_e64 v70, 0, -v70, s[28:29]
	v_cvt_pk_bf16_f32 v72, v69, v70
	v_add_f32_e32 v71, v70, v68
	v_lshlrev_b32_e32 v68, 16, v72
	v_sub_f32_e32 v68, v69, v68
	v_and_b32_e32 v69, 0xffff0000, v72
	v_sub_f32_e32 v69, v70, v69
	v_cvt_pk_bf16_f32 v68, v68, v69
	s_nop 0
	v_min_f32_e32 v94, 0x42c80000, v74
	v_add_u32_e32 v69, 0x52, v143
	v_cmp_lt_i32_e64 s[2:3], v69, v176
	v_exp_f32_e32 v69, v94
	s_or_b64 s[30:31], s[44:45], s[2:3]
	v_add_f32_e32 v69, 1.0, v69
	v_log_f32_e32 v69, v69
	s_nop 0
	v_cndmask_b32_e64 v69, 0, -v69, s[30:31]
	v_add_f32_e32 v70, v69, v71
; DI unsigned pk_bf16(float lo, float hi) { f32x2 v = {lo, hi}; bf2_t b = __builtin_convertvector(v, bf2_t); return __builtin_bit_cast(unsigned, b); }
; DI float bf_lo(unsigned u) { return __uint_as_float(u << 16); }
; DI float bf_hi(unsigned u) { return __uint_as_float(u & 0xffff0000u); }
; DI int crow(int i, int h) { return (i & 3) + 8 * (i >> 2) + 4 * h; }
; DI float fast_exp2(float x) { return __builtin_amdgcn_exp2f(x); }
; DI float fast_log2(float x) { return __builtin_amdgcn_logf(x); }
; template <int DQK, bool SB, bool SMAX>
; DI void attn_item(const Params& p, char* smem, int bh, int qb, float Mb) {
;     ...
;           for (int i2 = 0; i2 < 8; ++i2) {
;             float lk[2];
; #pragma unroll
;             for (int e = 0; e < 2; ++e) {
;               const int i = 2 * i2 + e;
;               const float z = fminf(st[kb][i], 100.f);
;               const int key = kb0 + kb * 32 + crow(i, h);
;               const bool valid = !diag || (key < query);
;               float l = -fast_log2(1.f + fast_exp2(z));
;               l = valid ? l : 0.f;
;               lk[e] = l;
;               tsum += l;
;               ca[kb][i] = z + carry;
;             }
;             const unsigned hp = pk_bf16(lk[0], lk[1]);
;             const unsigned lp = pk_bf16(lk[0] - bf_lo(hp), lk[1] - bf_hi(hp));
;             const int kk = kb * 2 + (i2 >> 2), w = i2 & 3;
;             hi[kk][2 * w] = (short)(hp & 0xffffu); hi[kk][2 * w + 1] = (short)(hp >> 16);
;             lo[kk][2 * w] = (short)(lp & 0xffffu); lo[kk][2 * w + 1] = (short)(lp >> 16);
;           }
	s_nop 0
	v_min_f32_e32 v95, 0x42c80000, v75
	v_add_u32_e32 v71, 0x53, v143
	v_cmp_lt_i32_e64 s[2:3], v71, v176
	v_exp_f32_e32 v71, v95
	s_or_b64 s[34:35], s[44:45], s[2:3]
	v_add_f32_e32 v71, 1.0, v71
	v_log_f32_e32 v71, v71
	s_nop 0
	v_cndmask_b32_e64 v71, 0, -v71, s[34:35]
	v_cvt_pk_bf16_f32 v73, v69, v71
	v_lshlrev_b32_e32 v74, 16, v73
	v_sub_f32_e32 v69, v69, v74
	v_and_b32_e32 v74, 0xffff0000, v73
	v_add_f32_e32 v70, v71, v70
	v_sub_f32_e32 v71, v71, v74
	v_cvt_pk_bf16_f32 v69, v69, v71
	s_nop 0
	v_min_f32_e32 v154, 0x42c80000, v76
	v_add_u32_e32 v71, 0x58, v143
	s_nop 0
	v_cmp_lt_i32_e64 s[2:3], v71, v176
	v_min_f32_e32 v155, 0x42c80000, v77
	v_add_u32_e32 v74, 0x59, v143
	s_or_b64 s[36:37], s[44:45], s[2:3]
	v_exp_f32_e32 v71, v154
	v_cmp_lt_i32_e64 s[2:3], v74, v176
	v_exp_f32_e32 v74, v155
	s_or_b64 s[38:39], s[44:45], s[2:3]
	v_add_f32_e32 v71, 1.0, v71
	v_log_f32_e32 v71, v71
	v_add_f32_e32 v74, 1.0, v74
	v_log_f32_e32 v74, v74
	v_cndmask_b32_e64 v71, 0, -v71, s[36:37]
	v_add_f32_e32 v70, v71, v70
	v_cndmask_b32_e64 v75, 0, -v74, s[38:39]
	v_cvt_pk_bf16_f32 v74, v71, v75
	v_add_f32_e32 v76, v75, v70
	v_lshlrev_b32_e32 v70, 16, v74
	v_sub_f32_e32 v70, v71, v70
	v_and_b32_e32 v71, 0xffff0000, v74
	v_sub_f32_e32 v71, v75, v71
	v_cvt_pk_bf16_f32 v70, v70, v71
	s_nop 0
	v_min_f32_e32 v158, 0x42c80000, v78
	v_add_u32_e32 v71, 0x5a, v143
	v_cmp_lt_i32_e64 s[2:3], v71, v176
	v_exp_f32_e32 v71, v158
	s_or_b64 s[40:41], s[44:45], s[2:3]
	v_add_f32_e32 v71, 1.0, v71
	v_log_f32_e32 v71, v71
	s_nop 0
	v_cndmask_b32_e64 v71, 0, -v71, s[40:41]
	v_add_f32_e32 v75, v71, v76
	s_nop 0
	v_min_f32_e32 v159, 0x42c80000, v79
	v_add_u32_e32 v76, 0x5b, v143
	v_cmp_lt_i32_e64 s[2:3], v76, v176
	v_exp_f32_e32 v76, v159
	s_or_b64 s[42:43], s[44:45], s[2:3]
	v_add_f32_e32 v76, 1.0, v76
	v_log_f32_e32 v76, v76
	s_nop 0
	v_cndmask_b32_e64 v76, 0, -v76, s[42:43]
	v_add_f32_e32 v77, v76, v75
	v_cvt_pk_bf16_f32 v75, v71, v76
	v_lshlrev_b32_e32 v78, 16, v75
	v_sub_f32_e32 v71, v71, v78
	v_and_b32_e32 v78, 0xffff0000, v75
	v_sub_f32_e32 v76, v76, v78
	v_cvt_pk_bf16_f32 v71, v71, v76
	v_add_u32_e32 v76, 0x60, v143
	v_cmp_lt_i32_e64 s[2:3], v76, v176
	s_or_b64 s[46:47], s[44:45], s[2:3]
	v_cmp_lt_i32_e64 s[2:3], v49, v176
	v_exp_f32_e32 v49, v157
	s_or_b64 s[48:49], s[44:45], s[2:3]
	v_cndmask_b32_e64 v48, 0, -v48, s[46:47]
	v_add_f32_e32 v76, v48, v77
	v_add_f32_e32 v49, 1.0, v49
	v_log_f32_e32 v49, v49
	s_nop 0
	v_cndmask_b32_e64 v49, 0, -v49, s[48:49]
	v_cvt_pk_bf16_f32 v136, v48, v49
	v_add_f32_e32 v77, v49, v76
	v_lshlrev_b32_e32 v76, 16, v136
	v_sub_f32_e32 v48, v48, v76
	v_and_b32_e32 v76, 0xffff0000, v136
	v_sub_f32_e32 v49, v49, v76
	v_cvt_pk_bf16_f32 v76, v48, v49
	s_nop 0
	v_min_f32_e32 v160, 0x42c80000, v50
	v_add_u32_e32 v48, 0x62, v143
	s_nop 0
	v_cmp_lt_i32_e64 s[2:3], v48, v176
	v_min_f32_e32 v161, 0x42c80000, v51
	v_add_u32_e32 v50, 0x63, v143
	s_or_b64 s[50:51], s[44:45], s[2:3]
	v_exp_f32_e32 v48, v160
	v_cmp_lt_i32_e64 s[2:3], v50, v176
	v_exp_f32_e32 v50, v161
	s_or_b64 s[52:53], s[44:45], s[2:3]
	v_add_f32_e32 v48, 1.0, v48
	v_log_f32_e32 v48, v48
	v_add_f32_e32 v50, 1.0, v50
	v_log_f32_e32 v50, v50
	v_cndmask_b32_e64 v48, 0, -v48, s[50:51]
	v_add_f32_e32 v49, v48, v77
	v_cndmask_b32_e64 v50, 0, -v50, s[52:53]
	v_cvt_pk_bf16_f32 v137, v48, v50
	v_lshlrev_b32_e32 v51, 16, v137
	v_sub_f32_e32 v48, v48, v51
	v_and_b32_e32 v51, 0xffff0000, v137
	v_add_f32_e32 v49, v50, v49
	v_sub_f32_e32 v50, v50, v51
	v_cvt_pk_bf16_f32 v77, v48, v50
	s_nop 0
	v_min_f32_e32 v162, 0x42c80000, v52
	v_add_u32_e32 v48, 0x68, v143
	s_nop 0
	v_cmp_lt_i32_e64 s[2:3], v48, v176
	v_min_f32_e32 v163, 0x42c80000, v53
	v_add_u32_e32 v50, 0x69, v143
	s_or_b64 s[54:55], s[44:45], s[2:3]
	v_exp_f32_e32 v48, v162
	v_cmp_lt_i32_e64 s[2:3], v50, v176
	v_exp_f32_e32 v50, v163
	s_or_b64 s[56:57], s[44:45], s[2:3]
	v_add_f32_e32 v48, 1.0, v48
	v_log_f32_e32 v48, v48
	v_add_f32_e32 v50, 1.0, v50
	v_log_f32_e32 v50, v50
	v_pk_add_f32 v[52:53], v[152:153], v[88:89] op_sel_hi:[0,1]
	v_cndmask_b32_e64 v48, 0, -v48, s[54:55]
	v_add_f32_e32 v49, v48, v49
	v_cndmask_b32_e64 v50, 0, -v50, s[56:57]
	v_cvt_pk_bf16_f32 v138, v48, v50
	v_lshlrev_b32_e32 v51, 16, v138
	v_sub_f32_e32 v48, v48, v51
	v_and_b32_e32 v51, 0xffff0000, v138
	v_add_f32_e32 v49, v50, v49
	v_sub_f32_e32 v50, v50, v51
	v_cvt_pk_bf16_f32 v78, v48, v50
	s_nop 0
	v_min_f32_e32 v164, 0x42c80000, v54
	v_add_u32_e32 v48, 0x6a, v143
	s_nop 0
	v_cmp_lt_i32_e64 s[2:3], v48, v176
	v_min_f32_e32 v165, 0x42c80000, v55
	v_add_u32_e32 v50, 0x6b, v143
	s_or_b64 s[58:59], s[44:45], s[2:3]
	v_exp_f32_e32 v48, v164
	v_cmp_lt_i32_e64 s[2:3], v50, v176
	v_exp_f32_e32 v50, v165
	s_or_b64 s[60:61], s[44:45], s[2:3]
	v_add_f32_e32 v48, 1.0, v48
	v_log_f32_e32 v48, v48
	v_add_f32_e32 v50, 1.0, v50
	v_log_f32_e32 v50, v50
	v_pk_add_f32 v[54:55], v[152:153], v[90:91] op_sel_hi:[0,1]
	v_cndmask_b32_e64 v48, 0, -v48, s[58:59]
	v_add_f32_e32 v49, v48, v49
	v_cndmask_b32_e64 v50, 0, -v50, s[60:61]
	v_cvt_pk_bf16_f32 v139, v48, v50
	v_lshlrev_b32_e32 v51, 16, v139
	v_sub_f32_e32 v48, v48, v51
	v_and_b32_e32 v51, 0xffff0000, v139
	v_add_f32_e32 v49, v50, v49
	v_sub_f32_e32 v50, v50, v51
	v_cvt_pk_bf16_f32 v79, v48, v50
	s_nop 0
	v_min_f32_e32 v166, 0x42c80000, v56
	v_add_u32_e32 v48, 0x70, v143
	s_nop 0
	v_cmp_lt_i32_e64 s[2:3], v48, v176
	v_min_f32_e32 v167, 0x42c80000, v57
	v_add_u32_e32 v50, 0x71, v143
	s_or_b64 s[62:63], s[44:45], s[2:3]
	v_exp_f32_e32 v48, v166
	v_cmp_lt_i32_e64 s[2:3], v50, v176
	v_exp_f32_e32 v50, v167
	s_or_b64 s[64:65], s[44:45], s[2:3]
	v_add_f32_e32 v48, 1.0, v48
	v_log_f32_e32 v48, v48
	v_add_f32_e32 v50, 1.0, v50
; template <int DQK, bool SB, bool SMAX>
; DI void attn_item(const Params& p, char* smem, int bh, int qb, float Mb) {
;     ...
;           for (int i2 = 0; i2 < 8; ++i2) {
;             float lk[2];
; #pragma unroll
;             for (int e = 0; e < 2; ++e) {
;               const int i = 2 * i2 + e;
;               const float z = fminf(st[kb][i], 100.f);
;               const int key = kb0 + kb * 32 + crow(i, h);
;               const bool valid = !diag || (key < query);
;               float l = -fast_log2(1.f + fast_exp2(z));
;               l = valid ? l : 0.f;
;               lk[e] = l;
;               tsum += l;
;               ca[kb][i] = z + carry;
;             }
;             const unsigned hp = pk_bf16(lk[0], lk[1]);
;             const unsigned lp = pk_bf16(lk[0] - bf_lo(hp), lk[1] - bf_hi(hp));
;             const int kk = kb * 2 + (i2 >> 2), w = i2 & 3;
;             hi[kk][2 * w] = (short)(hp & 0xffffu); hi[kk][2 * w + 1] = (short)(hp >> 16);
;             lo[kk][2 * w] = (short)(lp & 0xffffu); lo[kk][2 * w + 1] = (short)(lp >> 16);
;           }
;         tsum += other_half(tsum);
; #pragma unroll
;         for (int s = 0; s < 2; ++s) {
;           ca[0] = MFMA32(tri[s], hi[s], ca[0]);
;           ca[0] = MFMA32(tri[s], lo[s], ca[0]);
;           ca[0] = MFMA32(ones, hi[2 + s], ca[0]);
;           ca[0] = MFMA32(ones, lo[2 + s], ca[0]);
;           ca[1] = MFMA32(tri[s], hi[2 + s], ca[1]);
;           ca[1] = MFMA32(tri[s], lo[2 + s], ca[1]);
;         }
; #pragma unroll
;         for (int kb = 0; kb < 2; ++kb)
; #pragma unroll
;           for (int i = 0; i < 16; ++i) {
;             const int key = kb0 + kb * 32 + crow(i, h);
;             const bool valid = !diag || (key < query);
;             st[kb][i] = valid ? fast_exp2(ca[kb][i]) : 0.f;
;           }
;         carry += tsum;
;       }
; #pragma unroll
;       for (int kb = 0; kb < 2; ++kb)
; #pragma unroll
;         for (int s = 0; s < 2; ++s) {
;           u32x4 w;
; #pragma unroll
;           for (int e = 0; e < 4; ++e) w[e] = pk_bf16(st[kb][8 * s + 2 * e], st[kb][8 * s + 2 * e + 1]);
;           pk[kb * 2 + s] = __builtin_bit_cast(bf16x8, w);
;         }
; #pragma unroll
;       for (int kk = 0; kk < 4; ++kk)
; #pragma unroll
;         for (int db = 0; db < 2; ++db) {
;           const s16x4 v0 = __builtin_amdgcn_ds_read_tr16_b64_v4i16((lds_s16x4*)(vc + voff + (16 * kk) * VSTR + 32 * db));
	v_log_f32_e32 v50, v50
	v_pk_add_f32 v[56:57], v[152:153], v[92:93] op_sel_hi:[0,1]
	v_cndmask_b32_e64 v48, 0, -v48, s[62:63]
	v_add_f32_e32 v49, v48, v49
	v_cndmask_b32_e64 v50, 0, -v50, s[64:65]
	v_cvt_pk_bf16_f32 v140, v48, v50
	v_lshlrev_b32_e32 v51, 16, v140
	v_sub_f32_e32 v48, v48, v51
	v_and_b32_e32 v51, 0xffff0000, v140
	v_add_f32_e32 v49, v50, v49
	v_sub_f32_e32 v50, v50, v51
	v_cvt_pk_bf16_f32 v144, v48, v50
	s_nop 0
	v_min_f32_e32 v168, 0x42c80000, v58
	v_add_u32_e32 v48, 0x72, v143
	s_nop 0
	v_cmp_lt_i32_e64 s[2:3], v48, v176
	v_min_f32_e32 v169, 0x42c80000, v59
	v_add_u32_e32 v50, 0x73, v143
	s_or_b64 s[66:67], s[44:45], s[2:3]
	v_exp_f32_e32 v48, v168
	v_cmp_lt_i32_e64 s[2:3], v50, v176
	v_exp_f32_e32 v50, v169
	s_or_b64 s[68:69], s[44:45], s[2:3]
	v_add_f32_e32 v48, 1.0, v48
	v_log_f32_e32 v48, v48
	v_add_f32_e32 v50, 1.0, v50
	v_log_f32_e32 v50, v50
	v_pk_add_f32 v[58:59], v[152:153], v[94:95] op_sel_hi:[0,1]
	v_cndmask_b32_e64 v48, 0, -v48, s[66:67]
	v_add_f32_e32 v49, v48, v49
	v_cndmask_b32_e64 v50, 0, -v50, s[68:69]
	v_cvt_pk_bf16_f32 v141, v48, v50
	v_lshlrev_b32_e32 v51, 16, v141
	v_sub_f32_e32 v48, v48, v51
	v_and_b32_e32 v51, 0xffff0000, v141
	v_add_f32_e32 v49, v50, v49
	v_sub_f32_e32 v50, v50, v51
	v_cvt_pk_bf16_f32 v145, v48, v50
	s_nop 0
	v_min_f32_e32 v170, 0x42c80000, v60
	v_add_u32_e32 v48, 0x78, v143
	s_nop 0
	v_cmp_lt_i32_e64 s[2:3], v48, v176
	v_min_f32_e32 v171, 0x42c80000, v61
	v_add_u32_e32 v50, 0x79, v143
	s_or_b64 s[70:71], s[44:45], s[2:3]
	v_exp_f32_e32 v48, v170
	v_cmp_lt_i32_e64 s[2:3], v50, v176
	v_exp_f32_e32 v50, v171
	s_or_b64 s[72:73], s[44:45], s[2:3]
	v_add_f32_e32 v48, 1.0, v48
	v_log_f32_e32 v48, v48
	v_add_f32_e32 v50, 1.0, v50
	v_log_f32_e32 v50, v50
	v_pk_add_f32 v[60:61], v[152:153], v[154:155] op_sel_hi:[0,1]
	v_cndmask_b32_e64 v48, 0, -v48, s[70:71]
	v_add_f32_e32 v49, v48, v49
	v_cndmask_b32_e64 v50, 0, -v50, s[72:73]
	v_cvt_pk_bf16_f32 v142, v48, v50
	v_lshlrev_b32_e32 v51, 16, v142
	v_sub_f32_e32 v48, v48, v51
	v_and_b32_e32 v51, 0xffff0000, v142
	v_add_f32_e32 v49, v50, v49
	v_sub_f32_e32 v50, v50, v51
	v_cvt_pk_bf16_f32 v146, v48, v50
	s_nop 0
	v_min_f32_e32 v182, 0x42c80000, v62
	v_add_u32_e32 v48, 0x7a, v143
	s_nop 0
	v_cmp_lt_i32_e64 s[2:3], v48, v176
	v_min_f32_e32 v183, 0x42c80000, v63
	v_add_u32_e32 v50, 0x7b, v143
	s_or_b64 s[74:75], s[44:45], s[2:3]
	v_exp_f32_e32 v48, v182
	v_cmp_lt_i32_e64 s[2:3], v50, v176
	v_exp_f32_e32 v50, v183
	s_or_b64 s[44:45], s[44:45], s[2:3]
	v_add_f32_e32 v48, 1.0, v48
	v_log_f32_e32 v48, v48
	v_add_f32_e32 v50, 1.0, v50
	v_log_f32_e32 v50, v50
	v_pk_add_f32 v[62:63], v[152:153], v[158:159] op_sel_hi:[0,1]
	v_cndmask_b32_e64 v48, 0, -v48, s[74:75]
	v_add_f32_e32 v49, v48, v49
	v_cndmask_b32_e64 v50, 0, -v50, s[44:45]
	v_cvt_pk_bf16_f32 v143, v48, v50
	v_add_f32_e32 v184, v50, v49
	v_lshlrev_b32_e32 v49, 16, v143
	v_sub_f32_e32 v48, v48, v49
	v_and_b32_e32 v49, 0xffff0000, v143
	v_sub_f32_e32 v49, v50, v49
	v_cvt_pk_bf16_f32 v147, v48, v49
	v_mov_b32_e32 v48, v184
	v_mov_b32_e32 v49, v184
	s_nop 1
	v_permlane32_swap_b32_e32 v48, v49
	v_cndmask_b32_e64 v185, v48, v49, s[8:9]
	v_pk_add_f32 v[50:51], v[152:153], v[86:87] op_sel_hi:[0,1]
	v_pk_add_f32 v[48:49], v[152:153], v[84:85] op_sel_hi:[0,1]
	v_pk_add_f32 v[94:95], v[152:153], v[182:183] op_sel_hi:[0,1]
	v_pk_add_f32 v[92:93], v[152:153], v[170:171] op_sel_hi:[0,1]
	v_mfma_f32_32x32x16_bf16 v[48:63], v[96:99], v[80:83], v[48:63]
	v_add_f32_e64 v90, v152, v168
	v_add_f32_e64 v91, v152, v169
	v_add_f32_e64 v88, v152, v166
	v_add_f32_e64 v89, v152, v167
	v_add_f32_e64 v86, v152, v164
	v_add_f32_e64 v87, v152, v165
	v_pk_add_f32 v[84:85], v[152:153], v[162:163] op_sel_hi:[0,1]
	v_pk_add_f32 v[82:83], v[152:153], v[160:161] op_sel_hi:[0,1]
	v_pk_add_f32 v[80:81], v[152:153], v[156:157] op_sel_hi:[0,1]
	v_mfma_f32_32x32x16_bf16 v[48:63], v[96:99], v[64:67], v[48:63]
	v_mov_b64_e32 v[64:65], s[96:97]
	v_mov_b64_e32 v[66:67], s[98:99]
	s_nop 1
	v_mfma_f32_32x32x16_bf16 v[48:63], v[64:67], v[136:139], v[48:63]
	v_mfma_f32_32x32x16_bf16 v[48:63], v[64:67], v[76:79], v[48:63]
	v_mfma_f32_32x32x16_bf16 v[48:63], v[100:103], v[72:75], v[48:63]
	v_mfma_f32_32x32x16_bf16 v[48:63], v[100:103], v[68:71], v[48:63]
	v_mfma_f32_32x32x16_bf16 v[48:63], v[64:67], v[140:143], v[48:63]
	v_mfma_f32_32x32x16_bf16 v[48:63], v[64:67], v[144:147], v[48:63]
	v_mfma_f32_32x32x16_bf16 v[80:95], v[96:99], v[136:139], v[80:95]
	s_nop 10
	v_exp_f32_e32 v48, v48
	s_nop 0
	v_cndmask_b32_e32 v64, 0, v48, vcc
	v_exp_f32_e32 v48, v49
	v_mfma_f32_32x32x16_bf16 v[80:95], v[96:99], v[76:79], v[80:95]
	v_cndmask_b32_e64 v65, 0, v48, s[12:13]
	v_exp_f32_e32 v48, v50
	s_nop 0
	v_cndmask_b32_e64 v66, 0, v48, s[14:15]
	v_exp_f32_e32 v48, v51
	v_mfma_f32_32x32x16_bf16 v[80:95], v[100:103], v[140:143], v[80:95]
	v_cndmask_b32_e64 v67, 0, v48, s[16:17]
	v_exp_f32_e32 v48, v52
	s_nop 0
	v_cndmask_b32_e64 v68, 0, v48, s[18:19]
	v_exp_f32_e32 v48, v53
	v_mfma_f32_32x32x16_bf16 v[80:95], v[100:103], v[144:147], v[80:95]
	v_cndmask_b32_e64 v69, 0, v48, s[20:21]
	v_exp_f32_e32 v48, v54
	s_nop 0
	v_cndmask_b32_e64 v70, 0, v48, s[22:23]
	v_exp_f32_e32 v48, v55
	s_nop 6
	v_exp_f32_e32 v53, v85
	v_add_u32_e32 v85, v198, v200
	ds_read_b64_tr_b16 v[140:141], v85 offset:27648
	ds_read_b64_tr_b16 v[142:143], v85 offset:28800
	v_cndmask_b32_e64 v71, 0, v48, s[24:25]
	v_exp_f32_e32 v48, v56
	v_exp_f32_e32 v54, v86
	v_exp_f32_e32 v55, v87
	v_exp_f32_e32 v56, v88
	v_cndmask_b32_e64 v72, 0, v48, s[26:27]
	v_exp_f32_e32 v48, v57
	v_exp_f32_e32 v57, v89
	v_cvt_pk_bf16_f32 v86, v64, v65
	v_cvt_pk_bf16_f32 v87, v66, v67
	v_cndmask_b32_e64 v73, 0, v48, s[28:29]
	v_exp_f32_e32 v48, v58
	v_cvt_pk_bf16_f32 v88, v68, v69
	v_cvt_pk_bf16_f32 v89, v70, v71
	v_exp_f32_e32 v58, v90
	v_cndmask_b32_e64 v74, 0, v48, s[30:31]
	v_exp_f32_e32 v48, v59
	s_waitcnt lgkmcnt(0)
; #define MFMA32(a, b, c) __builtin_amdgcn_mfma_f32_32x32x16_bf16((a), (b), (c), 0, 0, 0)
; DI unsigned pk_bf16(float lo, float hi) { f32x2 v = {lo, hi}; bf2_t b = __builtin_convertvector(v, bf2_t); return __builtin_bit_cast(unsigned, b); }
; DI float bf_lo(unsigned u) { return __uint_as_float(u << 16); }
; DI float bf_hi(unsigned u) { return __uint_as_float(u & 0xffff0000u); }
; DI int crow(int i, int h) { return (i & 3) + 8 * (i >> 2) + 4 * h; }
; DI float fast_exp2(float x) { return __builtin_amdgcn_exp2f(x); }
; DI float fast_log2(float x) { return __builtin_amdgcn_logf(x); }
; template <int DQK, bool SB, bool SMAX>
; DI void attn_item(const Params& p, char* smem, int bh, int qb, float Mb) {
;     ...
;         for (int kb = 0; kb < 2; ++kb)
; #pragma unroll
;           for (int i2 = 0; i2 < 8; ++i2) {
;             float lk[2];
; #pragma unroll
;             for (int e = 0; e < 2; ++e) {
;               const int i = 2 * i2 + e;
;               const float z = fminf(st[kb][i], 100.f);
;               const int key = kb0 + kb * 32 + crow(i, h);
;               const bool valid = !diag || (key < query);
;               float l = -fast_log2(1.f + fast_exp2(z));
;               l = valid ? l : 0.f;
;               lk[e] = l;
;               tsum += l;
;               ca[kb][i] = z + carry;
;             }
;             const unsigned hp = pk_bf16(lk[0], lk[1]);
;             const unsigned lp = pk_bf16(lk[0] - bf_lo(hp), lk[1] - bf_hi(hp));
;             const int kk = kb * 2 + (i2 >> 2), w = i2 & 3;
;             hi[kk][2 * w] = (short)(hp & 0xffffu); hi[kk][2 * w + 1] = (short)(hp >> 16);
;             lo[kk][2 * w] = (short)(lp & 0xffffu); lo[kk][2 * w + 1] = (short)(lp >> 16);
;           }
;     ...
; #pragma unroll
;       for (int kk = 0; kk < 4; ++kk)
; #pragma unroll
;         for (int db = 0; db < 2; ++db) {
;           const s16x4 v0 = __builtin_amdgcn_ds_read_tr16_b64_v4i16((lds_s16x4*)(vc + voff + (16 * kk) * VSTR + 32 * db));
;           const s16x4 v1 = __builtin_amdgcn_ds_read_tr16_b64_v4i16((lds_s16x4*)(vc + voff + (16 * kk + 8) * VSTR + 32 * db));
;           const bf16x8 vf = __builtin_shufflevector(v0, v1, 0, 1, 2, 3, 4, 5, 6, 7);
;           O[db] = MFMA32(vf, pk[kk], O[db]);
;         }
	v_mfma_f32_32x32x16_bf16 v[32:47], v[140:143], v[86:89], v[32:47]
	ds_read_b64_tr_b16 v[140:141], v85 offset:27712
	ds_read_b64_tr_b16 v[142:143], v85 offset:28864
	v_exp_f32_e32 v59, v91
	v_cndmask_b32_e64 v75, 0, v48, s[34:35]
	v_exp_f32_e32 v48, v60
	v_exp_f32_e32 v60, v92
	v_cvt_pk_bf16_f32 v90, v72, v73
	v_cvt_pk_bf16_f32 v91, v74, v75
	v_cndmask_b32_e64 v76, 0, v48, s[36:37]
	v_exp_f32_e32 v48, v61
	s_waitcnt lgkmcnt(0)
	v_mfma_f32_32x32x16_bf16 v[16:31], v[140:143], v[86:89], v[16:31]
	ds_read_b64_tr_b16 v[86:87], v85 offset:29952
	ds_read_b64_tr_b16 v[88:89], v85 offset:31104
	v_exp_f32_e32 v61, v93
	v_cndmask_b32_e64 v77, 0, v48, s[38:39]
	v_exp_f32_e32 v48, v62
	v_cvt_pk_bf16_f32 v92, v76, v77
	v_exp_f32_e32 v49, v81
	v_exp_f32_e32 v50, v82
	v_cndmask_b32_e64 v78, 0, v48, s[40:41]
	v_exp_f32_e32 v48, v63
	v_exp_f32_e32 v51, v83
	v_exp_f32_e32 v52, v84
	v_cndmask_b32_e64 v49, 0, v49, s[48:49]
	v_cndmask_b32_e64 v79, 0, v48, s[42:43]
	v_cvt_pk_bf16_f32 v93, v78, v79
	v_exp_f32_e32 v48, v80
	v_cndmask_b32_e64 v50, 0, v50, s[50:51]
	s_waitcnt lgkmcnt(0)
	v_mfma_f32_32x32x16_bf16 v[32:47], v[86:89], v[90:93], v[32:47]
	ds_read_b64_tr_b16 v[86:87], v85 offset:30016
	ds_read_b64_tr_b16 v[88:89], v85 offset:31168
	v_cndmask_b32_e64 v48, 0, v48, s[46:47]
	v_cndmask_b32_e64 v51, 0, v51, s[52:53]
	v_cndmask_b32_e64 v52, 0, v52, s[54:55]
	v_cndmask_b32_e64 v53, 0, v53, s[56:57]
	v_cndmask_b32_e64 v54, 0, v54, s[58:59]
	v_cndmask_b32_e64 v55, 0, v55, s[60:61]
	s_waitcnt lgkmcnt(0)
	v_mfma_f32_32x32x16_bf16 v[16:31], v[86:89], v[90:93], v[16:31]
	ds_read_b64_tr_b16 v[86:87], v85 offset:32256
	ds_read_b64_tr_b16 v[88:89], v85 offset:33408
	v_cvt_pk_bf16_f32 v136, v48, v49
	v_cvt_pk_bf16_f32 v137, v50, v51
	v_cvt_pk_bf16_f32 v138, v52, v53
	v_cvt_pk_bf16_f32 v139, v54, v55
	v_exp_f32_e32 v62, v94
	v_exp_f32_e32 v63, v95
	s_waitcnt lgkmcnt(0)
	v_mfma_f32_32x32x16_bf16 v[32:47], v[86:89], v[136:139], v[32:47]
	ds_read_b64_tr_b16 v[86:87], v85 offset:32320
	ds_read_b64_tr_b16 v[88:89], v85 offset:33472
	v_cndmask_b32_e64 v56, 0, v56, s[62:63]
	v_cndmask_b32_e64 v57, 0, v57, s[64:65]
	v_cndmask_b32_e64 v58, 0, v58, s[66:67]
	v_cndmask_b32_e64 v59, 0, v59, s[68:69]
	v_cndmask_b32_e64 v60, 0, v60, s[70:71]
	v_cndmask_b32_e64 v61, 0, v61, s[72:73]
	s_waitcnt lgkmcnt(0)
	v_mfma_f32_32x32x16_bf16 v[16:31], v[86:89], v[136:139], v[16:31]
	ds_read_b64_tr_b16 v[86:87], v85 offset:34560
	ds_read_b64_tr_b16 v[88:89], v85 offset:35712
	v_cndmask_b32_e64 v62, 0, v62, s[74:75]
	v_cndmask_b32_e64 v63, 0, v63, s[44:45]
	v_cvt_pk_bf16_f32 v80, v56, v57
	v_cvt_pk_bf16_f32 v81, v58, v59
	v_cvt_pk_bf16_f32 v82, v60, v61
	v_cvt_pk_bf16_f32 v83, v62, v63
	v_add_f32_e32 v84, v184, v185
	v_add_f32_e32 v152, v152, v84
	s_waitcnt lgkmcnt(0)
	v_mfma_f32_32x32x16_bf16 v[32:47], v[86:89], v[80:83], v[32:47]
	ds_read_b64_tr_b16 v[86:87], v85 offset:34624
	ds_read_b64_tr_b16 v[88:89], v85 offset:35776
	s_waitcnt lgkmcnt(0)
	v_mfma_f32_32x32x16_bf16 v[16:31], v[86:89], v[80:83], v[16:31]
	s_branch .LBB0_444
.Lsbf_2:
	s_nop 0
	v_add_u32_e32 v143, s78, v197
	v_min_f32_e32 v84, 0x42c80000, v64
	s_nop 0
	v_exp_f32_e32 v64, v84
	v_min_f32_e32 v85, 0x42c80000, v65
	s_nop 0
	s_nop 0
	v_exp_f32_e32 v65, v85
	v_add_f32_e32 v64, 1.0, v64
	v_log_f32_e32 v64, v64
	s_nop 0
	v_add_f32_e32 v65, 1.0, v65
	v_log_f32_e32 v65, v65
	s_nop 0
	s_nop 0
	s_nop 0
	s_nop 0
	v_xor_b32_e32 v64, 0x80000000, v64
	v_add_f32_e32 v80, 0, v64
	v_xor_b32_e32 v65, 0x80000000, v65
	v_add_f32_e32 v81, v65, v80
	v_cvt_pk_bf16_f32 v80, v64, v65
	v_lshlrev_b32_e32 v82, 16, v80
	v_sub_f32_e32 v64, v64, v82
	v_and_b32_e32 v82, 0xffff0000, v80
	v_sub_f32_e32 v65, v65, v82
	v_cvt_pk_bf16_f32 v64, v64, v65
	s_nop 0
	v_min_f32_e32 v86, 0x42c80000, v66
	s_nop 0
	s_nop 0
	s_nop 0
	v_min_f32_e32 v87, 0x42c80000, v67
	s_nop 0
	s_nop 0
	v_exp_f32_e32 v65, v86
	s_nop 0
	v_exp_f32_e32 v67, v87
	s_nop 0
	v_add_f32_e32 v65, 1.0, v65
	v_log_f32_e32 v65, v65
	v_add_f32_e32 v67, 1.0, v67
	v_log_f32_e32 v67, v67
	s_nop 0
	v_xor_b32_e32 v65, 0x80000000, v65
	v_add_f32_e32 v66, v65, v81
	v_xor_b32_e32 v67, 0x80000000, v67
	v_cvt_pk_bf16_f32 v81, v65, v67
	v_lshlrev_b32_e32 v82, 16, v81
	v_sub_f32_e32 v65, v65, v82
	v_and_b32_e32 v82, 0xffff0000, v81
	v_add_f32_e32 v66, v67, v66
	v_sub_f32_e32 v67, v67, v82
	v_cvt_pk_bf16_f32 v65, v65, v67
	s_nop 0
	v_min_f32_e32 v88, 0x42c80000, v68
	s_nop 0
	s_nop 0
	s_nop 0
	v_min_f32_e32 v89, 0x42c80000, v69
	s_nop 0
	s_nop 0
	v_exp_f32_e32 v67, v88
	s_nop 0
	v_exp_f32_e32 v68, v89
	s_nop 0
	v_add_f32_e32 v67, 1.0, v67
	v_log_f32_e32 v67, v67
	v_add_f32_e32 v68, 1.0, v68
	v_log_f32_e32 v68, v68
	s_nop 0
	v_xor_b32_e32 v67, 0x80000000, v67
	v_add_f32_e32 v66, v67, v66
	v_xor_b32_e32 v68, 0x80000000, v68
	v_cvt_pk_bf16_f32 v82, v67, v68
	v_add_f32_e32 v69, v68, v66
	v_lshlrev_b32_e32 v66, 16, v82
	v_sub_f32_e32 v66, v67, v66
	v_and_b32_e32 v67, 0xffff0000, v82
	v_sub_f32_e32 v67, v68, v67
	v_cvt_pk_bf16_f32 v66, v66, v67
	s_nop 0
	v_min_f32_e32 v90, 0x42c80000, v70
	s_nop 0
	s_nop 0
	v_exp_f32_e32 v67, v90
	s_nop 0
	v_min_f32_e32 v156, 0x42c80000, v48
	v_min_f32_e32 v157, 0x42c80000, v49
	v_add_f32_e32 v67, 1.0, v67
	v_log_f32_e32 v67, v67
	s_nop 0
	v_exp_f32_e32 v48, v156
	s_mov_b32 s97, s96
	v_xor_b32_e32 v67, 0x80000000, v67
	v_add_f32_e32 v68, v67, v69
	s_nop 0
	v_min_f32_e32 v91, 0x42c80000, v71
	s_nop 0
	s_nop 0
	v_exp_f32_e32 v69, v91
	s_nop 0
	v_add_f32_e32 v48, 1.0, v48
	v_log_f32_e32 v48, v48
	v_add_f32_e32 v69, 1.0, v69
	v_log_f32_e32 v69, v69
	s_mov_b32 s98, s96
	s_mov_b32 s99, s96
	v_xor_b32_e32 v69, 0x80000000, v69
	v_cvt_pk_bf16_f32 v83, v67, v69
	v_lshlrev_b32_e32 v70, 16, v83
; DI unsigned pk_bf16(float lo, float hi) { f32x2 v = {lo, hi}; bf2_t b = __builtin_convertvector(v, bf2_t); return __builtin_bit_cast(unsigned, b); }
; DI float bf_lo(unsigned u) { return __uint_as_float(u << 16); }
; DI float bf_hi(unsigned u) { return __uint_as_float(u & 0xffff0000u); }
; DI int crow(int i, int h) { return (i & 3) + 8 * (i >> 2) + 4 * h; }
; DI float fast_exp2(float x) { return __builtin_amdgcn_exp2f(x); }
; DI float fast_log2(float x) { return __builtin_amdgcn_logf(x); }
; template <int DQK, bool SB, bool SMAX>
; DI void attn_item(const Params& p, char* smem, int bh, int qb, float Mb) {
;     ...
;         for (int kb = 0; kb < 2; ++kb)
; #pragma unroll
;           for (int i2 = 0; i2 < 8; ++i2) {
;             float lk[2];
; #pragma unroll
;             for (int e = 0; e < 2; ++e) {
;               const int i = 2 * i2 + e;
;               const float z = fminf(st[kb][i], 100.f);
;               const int key = kb0 + kb * 32 + crow(i, h);
;               const bool valid = !diag || (key < query);
;               float l = -fast_log2(1.f + fast_exp2(z));
;               l = valid ? l : 0.f;
;               lk[e] = l;
;               tsum += l;
;               ca[kb][i] = z + carry;
;             }
;             const unsigned hp = pk_bf16(lk[0], lk[1]);
;             const unsigned lp = pk_bf16(lk[0] - bf_lo(hp), lk[1] - bf_hi(hp));
;             const int kk = kb * 2 + (i2 >> 2), w = i2 & 3;
;             hi[kk][2 * w] = (short)(hp & 0xffffu); hi[kk][2 * w + 1] = (short)(hp >> 16);
;             lo[kk][2 * w] = (short)(lp & 0xffffu); lo[kk][2 * w + 1] = (short)(lp >> 16);
;           }
	v_sub_f32_e32 v67, v67, v70
	v_and_b32_e32 v70, 0xffff0000, v83
	v_add_f32_e32 v68, v69, v68
	v_sub_f32_e32 v69, v69, v70
	v_cvt_pk_bf16_f32 v67, v67, v69
	s_nop 0
	v_min_f32_e32 v92, 0x42c80000, v72
	s_nop 0
	s_nop 0
	s_nop 0
	v_min_f32_e32 v93, 0x42c80000, v73
	s_nop 0
	s_nop 0
	v_exp_f32_e32 v69, v92
	s_nop 0
	v_exp_f32_e32 v70, v93
	s_nop 0
	v_add_f32_e32 v69, 1.0, v69
	v_log_f32_e32 v69, v69
	v_add_f32_e32 v70, 1.0, v70
	v_log_f32_e32 v70, v70
	v_xor_b32_e32 v69, 0x80000000, v69
	v_add_f32_e32 v68, v69, v68
	v_xor_b32_e32 v70, 0x80000000, v70
	v_cvt_pk_bf16_f32 v72, v69, v70
	v_add_f32_e32 v71, v70, v68
	v_lshlrev_b32_e32 v68, 16, v72
	v_sub_f32_e32 v68, v69, v68
	v_and_b32_e32 v69, 0xffff0000, v72
	v_sub_f32_e32 v69, v70, v69
	v_cvt_pk_bf16_f32 v68, v68, v69
	s_nop 0
	v_min_f32_e32 v94, 0x42c80000, v74
	s_nop 0
	s_nop 0
	v_exp_f32_e32 v69, v94
	s_nop 0
	v_add_f32_e32 v69, 1.0, v69
	v_log_f32_e32 v69, v69
	s_nop 0
	v_xor_b32_e32 v69, 0x80000000, v69
	v_add_f32_e32 v70, v69, v71
	s_nop 0
	v_min_f32_e32 v95, 0x42c80000, v75
	s_nop 0
	s_nop 0
	v_exp_f32_e32 v71, v95
	s_nop 0
	v_add_f32_e32 v71, 1.0, v71
	v_log_f32_e32 v71, v71
	s_nop 0
	v_xor_b32_e32 v71, 0x80000000, v71
	v_cvt_pk_bf16_f32 v73, v69, v71
	v_lshlrev_b32_e32 v74, 16, v73
	v_sub_f32_e32 v69, v69, v74
	v_and_b32_e32 v74, 0xffff0000, v73
	v_add_f32_e32 v70, v71, v70
	v_sub_f32_e32 v71, v71, v74
	v_cvt_pk_bf16_f32 v69, v69, v71
	s_nop 0
	v_min_f32_e32 v154, 0x42c80000, v76
	s_nop 0
	s_nop 0
	s_nop 0
	v_min_f32_e32 v155, 0x42c80000, v77
	s_nop 0
	s_nop 0
	v_exp_f32_e32 v71, v154
	s_nop 0
	v_exp_f32_e32 v74, v155
	s_nop 0
	v_add_f32_e32 v71, 1.0, v71
	v_log_f32_e32 v71, v71
	v_add_f32_e32 v74, 1.0, v74
	v_log_f32_e32 v74, v74
	v_xor_b32_e32 v71, 0x80000000, v71
	v_add_f32_e32 v70, v71, v70
	v_xor_b32_e32 v75, 0x80000000, v74
	v_cvt_pk_bf16_f32 v74, v71, v75
	v_add_f32_e32 v76, v75, v70
	v_lshlrev_b32_e32 v70, 16, v74
	v_sub_f32_e32 v70, v71, v70
	v_and_b32_e32 v71, 0xffff0000, v74
	v_sub_f32_e32 v71, v75, v71
	v_cvt_pk_bf16_f32 v70, v70, v71
	s_nop 0
	v_min_f32_e32 v158, 0x42c80000, v78
	s_nop 0
	s_nop 0
	v_exp_f32_e32 v71, v158
	s_nop 0
	v_add_f32_e32 v71, 1.0, v71
	v_log_f32_e32 v71, v71
	s_nop 0
	v_xor_b32_e32 v71, 0x80000000, v71
	v_add_f32_e32 v75, v71, v76
	s_nop 0
	v_min_f32_e32 v159, 0x42c80000, v79
	s_nop 0
	s_nop 0
	v_exp_f32_e32 v76, v159
	s_nop 0
	v_add_f32_e32 v76, 1.0, v76
	v_log_f32_e32 v76, v76
	s_nop 0
	v_xor_b32_e32 v76, 0x80000000, v76
	v_add_f32_e32 v77, v76, v75
	v_cvt_pk_bf16_f32 v75, v71, v76
	v_lshlrev_b32_e32 v78, 16, v75
	v_sub_f32_e32 v71, v71, v78
	v_and_b32_e32 v78, 0xffff0000, v75
	v_sub_f32_e32 v76, v76, v78
	v_cvt_pk_bf16_f32 v71, v71, v76
	s_nop 0
	s_nop 0
	s_nop 0
	s_nop 0
	v_exp_f32_e32 v49, v157
	s_nop 0
	v_xor_b32_e32 v48, 0x80000000, v48
	v_add_f32_e32 v76, v48, v77
	v_add_f32_e32 v49, 1.0, v49
	v_log_f32_e32 v49, v49
	s_nop 0
	v_xor_b32_e32 v49, 0x80000000, v49
	v_cvt_pk_bf16_f32 v136, v48, v49
	v_add_f32_e32 v77, v49, v76
	v_lshlrev_b32_e32 v76, 16, v136
	v_sub_f32_e32 v48, v48, v76
	v_and_b32_e32 v76, 0xffff0000, v136
	v_sub_f32_e32 v49, v49, v76
	v_cvt_pk_bf16_f32 v76, v48, v49
	s_nop 0
	v_min_f32_e32 v160, 0x42c80000, v50
	s_nop 0
	s_nop 0
	s_nop 0
	v_min_f32_e32 v161, 0x42c80000, v51
	s_nop 0
	s_nop 0
	v_exp_f32_e32 v48, v160
	s_nop 0
	v_exp_f32_e32 v50, v161
	s_nop 0
	v_add_f32_e32 v48, 1.0, v48
	v_log_f32_e32 v48, v48
	v_add_f32_e32 v50, 1.0, v50
	v_log_f32_e32 v50, v50
	v_xor_b32_e32 v48, 0x80000000, v48
	v_add_f32_e32 v49, v48, v77
	v_xor_b32_e32 v50, 0x80000000, v50
	v_cvt_pk_bf16_f32 v137, v48, v50
	v_lshlrev_b32_e32 v51, 16, v137
	v_sub_f32_e32 v48, v48, v51
	v_and_b32_e32 v51, 0xffff0000, v137
	v_add_f32_e32 v49, v50, v49
	v_sub_f32_e32 v50, v50, v51
	v_cvt_pk_bf16_f32 v77, v48, v50
	s_nop 0
	v_min_f32_e32 v162, 0x42c80000, v52
	s_nop 0
	s_nop 0
	s_nop 0
	v_min_f32_e32 v163, 0x42c80000, v53
	s_nop 0
	s_nop 0
	v_exp_f32_e32 v48, v162
	s_nop 0
	v_exp_f32_e32 v50, v163
	s_nop 0
	v_add_f32_e32 v48, 1.0, v48
	v_log_f32_e32 v48, v48
	v_add_f32_e32 v50, 1.0, v50
	v_log_f32_e32 v50, v50
	v_pk_add_f32 v[52:53], v[152:153], v[88:89] op_sel_hi:[0,1]
	v_xor_b32_e32 v48, 0x80000000, v48
	v_add_f32_e32 v49, v48, v49
	v_xor_b32_e32 v50, 0x80000000, v50
	v_cvt_pk_bf16_f32 v138, v48, v50
	v_lshlrev_b32_e32 v51, 16, v138
	v_sub_f32_e32 v48, v48, v51
	v_and_b32_e32 v51, 0xffff0000, v138
	v_add_f32_e32 v49, v50, v49
	v_sub_f32_e32 v50, v50, v51
	v_cvt_pk_bf16_f32 v78, v48, v50
	s_nop 0
	v_min_f32_e32 v164, 0x42c80000, v54
	s_nop 0
	s_nop 0
	s_nop 0
	v_min_f32_e32 v165, 0x42c80000, v55
	s_nop 0
	s_nop 0
	v_exp_f32_e32 v48, v164
	s_nop 0
	v_exp_f32_e32 v50, v165
	s_nop 0
	v_add_f32_e32 v48, 1.0, v48
	v_log_f32_e32 v48, v48
	v_add_f32_e32 v50, 1.0, v50
	v_log_f32_e32 v50, v50
	v_pk_add_f32 v[54:55], v[152:153], v[90:91] op_sel_hi:[0,1]
	v_xor_b32_e32 v48, 0x80000000, v48
	v_add_f32_e32 v49, v48, v49
	v_xor_b32_e32 v50, 0x80000000, v50
	v_cvt_pk_bf16_f32 v139, v48, v50
	v_lshlrev_b32_e32 v51, 16, v139
	v_sub_f32_e32 v48, v48, v51
	v_and_b32_e32 v51, 0xffff0000, v139
	v_add_f32_e32 v49, v50, v49
	v_sub_f32_e32 v50, v50, v51
	v_cvt_pk_bf16_f32 v79, v48, v50
	s_nop 0
	v_min_f32_e32 v166, 0x42c80000, v56
	s_nop 0
	s_nop 0
	s_nop 0
	v_min_f32_e32 v167, 0x42c80000, v57
	s_nop 0
	s_nop 0
	v_exp_f32_e32 v48, v166
	s_nop 0
	v_exp_f32_e32 v50, v167
	s_nop 0
	v_add_f32_e32 v48, 1.0, v48
	v_log_f32_e32 v48, v48
	v_add_f32_e32 v50, 1.0, v50
	v_log_f32_e32 v50, v50
	v_pk_add_f32 v[56:57], v[152:153], v[92:93] op_sel_hi:[0,1]
	v_xor_b32_e32 v48, 0x80000000, v48
	v_add_f32_e32 v49, v48, v49
	v_xor_b32_e32 v50, 0x80000000, v50
	v_cvt_pk_bf16_f32 v140, v48, v50
; #define MFMA32(a, b, c) __builtin_amdgcn_mfma_f32_32x32x16_bf16((a), (b), (c), 0, 0, 0)
; DI unsigned pk_bf16(float lo, float hi) { f32x2 v = {lo, hi}; bf2_t b = __builtin_convertvector(v, bf2_t); return __builtin_bit_cast(unsigned, b); }
; template <int DQK, bool SB, bool SMAX>
; DI void attn_item(const Params& p, char* smem, int bh, int qb, float Mb) {
;     ...
;             const unsigned hp = pk_bf16(lk[0], lk[1]);
;             const unsigned lp = pk_bf16(lk[0] - bf_lo(hp), lk[1] - bf_hi(hp));
;             const int kk = kb * 2 + (i2 >> 2), w = i2 & 3;
;             hi[kk][2 * w] = (short)(hp & 0xffffu); hi[kk][2 * w + 1] = (short)(hp >> 16);
;             lo[kk][2 * w] = (short)(lp & 0xffffu); lo[kk][2 * w + 1] = (short)(lp >> 16);
;           }
;         tsum += other_half(tsum);
; #pragma unroll
;         for (int s = 0; s < 2; ++s) {
;           ca[0] = MFMA32(tri[s], hi[s], ca[0]);
;           ca[0] = MFMA32(tri[s], lo[s], ca[0]);
;           ca[0] = MFMA32(ones, hi[2 + s], ca[0]);
;           ca[0] = MFMA32(ones, lo[2 + s], ca[0]);
;           ca[1] = MFMA32(tri[s], hi[2 + s], ca[1]);
;           ca[1] = MFMA32(tri[s], lo[2 + s], ca[1]);
;         }
; #pragma unroll
;         for (int kb = 0; kb < 2; ++kb)
; #pragma unroll
;           for (int i = 0; i < 16; ++i) {
;             const int key = kb0 + kb * 32 + crow(i, h);
;             const bool valid = !diag || (key < query);
;             st[kb][i] = valid ? fast_exp2(ca[kb][i]) : 0.f;
;           }
;         carry += tsum;
;       }
; #pragma unroll
;       for (int kb = 0; kb < 2; ++kb)
; #pragma unroll
;         for (int s = 0; s < 2; ++s) {
;           u32x4 w;
; #pragma unroll
;           for (int e = 0; e < 4; ++e) w[e] = pk_bf16(st[kb][8 * s + 2 * e], st[kb][8 * s + 2 * e + 1]);
;           pk[kb * 2 + s] = __builtin_bit_cast(bf16x8, w);
;         }
; #pragma unroll
;       for (int kk = 0; kk < 4; ++kk)
; #pragma unroll
;         for (int db = 0; db < 2; ++db) {
;           const s16x4 v0 = __builtin_amdgcn_ds_read_tr16_b64_v4i16((lds_s16x4*)(vc + voff + (16 * kk) * VSTR + 32 * db));
;           const s16x4 v1 = __builtin_amdgcn_ds_read_tr16_b64_v4i16((lds_s16x4*)(vc + voff + (16 * kk + 8) * VSTR + 32 * db));
;           const bf16x8 vf = __builtin_shufflevector(v0, v1, 0, 1, 2, 3, 4, 5, 6, 7);
;           O[db] = MFMA32(vf, pk[kk], O[db]);
	v_lshlrev_b32_e32 v51, 16, v140
	v_sub_f32_e32 v48, v48, v51
	v_and_b32_e32 v51, 0xffff0000, v140
	v_add_f32_e32 v49, v50, v49
	v_sub_f32_e32 v50, v50, v51
	v_cvt_pk_bf16_f32 v144, v48, v50
	s_nop 0
	v_min_f32_e32 v168, 0x42c80000, v58
	s_nop 0
	s_nop 0
	s_nop 0
	v_min_f32_e32 v169, 0x42c80000, v59
	s_nop 0
	s_nop 0
	v_exp_f32_e32 v48, v168
	s_nop 0
	v_exp_f32_e32 v50, v169
	s_nop 0
	v_add_f32_e32 v48, 1.0, v48
	v_log_f32_e32 v48, v48
	v_add_f32_e32 v50, 1.0, v50
	v_log_f32_e32 v50, v50
	v_pk_add_f32 v[58:59], v[152:153], v[94:95] op_sel_hi:[0,1]
	v_xor_b32_e32 v48, 0x80000000, v48
	v_add_f32_e32 v49, v48, v49
	v_xor_b32_e32 v50, 0x80000000, v50
	v_cvt_pk_bf16_f32 v141, v48, v50
	v_lshlrev_b32_e32 v51, 16, v141
	v_sub_f32_e32 v48, v48, v51
	v_and_b32_e32 v51, 0xffff0000, v141
	v_add_f32_e32 v49, v50, v49
	v_sub_f32_e32 v50, v50, v51
	v_cvt_pk_bf16_f32 v145, v48, v50
	s_nop 0
	v_min_f32_e32 v170, 0x42c80000, v60
	s_nop 0
	s_nop 0
	s_nop 0
	v_min_f32_e32 v171, 0x42c80000, v61
	s_nop 0
	s_nop 0
	v_exp_f32_e32 v48, v170
	s_nop 0
	v_exp_f32_e32 v50, v171
	s_nop 0
	v_add_f32_e32 v48, 1.0, v48
	v_log_f32_e32 v48, v48
	v_add_f32_e32 v50, 1.0, v50
	v_log_f32_e32 v50, v50
	v_pk_add_f32 v[60:61], v[152:153], v[154:155] op_sel_hi:[0,1]
	v_xor_b32_e32 v48, 0x80000000, v48
	v_add_f32_e32 v49, v48, v49
	v_xor_b32_e32 v50, 0x80000000, v50
	v_cvt_pk_bf16_f32 v142, v48, v50
	v_lshlrev_b32_e32 v51, 16, v142
	v_sub_f32_e32 v48, v48, v51
	v_and_b32_e32 v51, 0xffff0000, v142
	v_add_f32_e32 v49, v50, v49
	v_sub_f32_e32 v50, v50, v51
	v_cvt_pk_bf16_f32 v146, v48, v50
	s_nop 0
	v_min_f32_e32 v182, 0x42c80000, v62
	s_nop 0
	s_nop 0
	s_nop 0
	v_min_f32_e32 v183, 0x42c80000, v63
	s_nop 0
	s_nop 0
	v_exp_f32_e32 v48, v182
	s_nop 0
	v_exp_f32_e32 v50, v183
	s_nop 0
	v_add_f32_e32 v48, 1.0, v48
	v_log_f32_e32 v48, v48
	v_add_f32_e32 v50, 1.0, v50
	v_log_f32_e32 v50, v50
	v_pk_add_f32 v[62:63], v[152:153], v[158:159] op_sel_hi:[0,1]
	v_xor_b32_e32 v48, 0x80000000, v48
	v_add_f32_e32 v49, v48, v49
	v_xor_b32_e32 v50, 0x80000000, v50
	v_cvt_pk_bf16_f32 v143, v48, v50
	v_add_f32_e32 v184, v50, v49
	v_lshlrev_b32_e32 v49, 16, v143
	v_sub_f32_e32 v48, v48, v49
	v_and_b32_e32 v49, 0xffff0000, v143
	v_sub_f32_e32 v49, v50, v49
	v_cvt_pk_bf16_f32 v147, v48, v49
	v_mov_b32_e32 v48, v184
	v_mov_b32_e32 v49, v184
	s_nop 1
	v_permlane32_swap_b32_e32 v48, v49
	v_cndmask_b32_e64 v185, v48, v49, s[8:9]
	v_pk_add_f32 v[50:51], v[152:153], v[86:87] op_sel_hi:[0,1]
	v_pk_add_f32 v[48:49], v[152:153], v[84:85] op_sel_hi:[0,1]
	v_pk_add_f32 v[94:95], v[152:153], v[182:183] op_sel_hi:[0,1]
	v_pk_add_f32 v[92:93], v[152:153], v[170:171] op_sel_hi:[0,1]
	v_mfma_f32_32x32x16_bf16 v[48:63], v[96:99], v[80:83], v[48:63]
	v_add_f32_e64 v90, v152, v168
	v_add_f32_e64 v91, v152, v169
	v_add_f32_e64 v88, v152, v166
	v_add_f32_e64 v89, v152, v167
	v_add_f32_e64 v86, v152, v164
	v_add_f32_e64 v87, v152, v165
	v_pk_add_f32 v[84:85], v[152:153], v[162:163] op_sel_hi:[0,1]
	v_pk_add_f32 v[82:83], v[152:153], v[160:161] op_sel_hi:[0,1]
	v_pk_add_f32 v[80:81], v[152:153], v[156:157] op_sel_hi:[0,1]
	v_mfma_f32_32x32x16_bf16 v[48:63], v[96:99], v[64:67], v[48:63]
	v_mov_b64_e32 v[64:65], s[96:97]
	v_mov_b64_e32 v[66:67], s[98:99]
	s_nop 1
	v_mfma_f32_32x32x16_bf16 v[48:63], v[64:67], v[136:139], v[48:63]
	v_mfma_f32_32x32x16_bf16 v[48:63], v[64:67], v[76:79], v[48:63]
	v_mfma_f32_32x32x16_bf16 v[48:63], v[100:103], v[72:75], v[48:63]
	v_mfma_f32_32x32x16_bf16 v[48:63], v[100:103], v[68:71], v[48:63]
	v_mfma_f32_32x32x16_bf16 v[48:63], v[64:67], v[140:143], v[48:63]
	v_mfma_f32_32x32x16_bf16 v[48:63], v[64:67], v[144:147], v[48:63]
	v_mfma_f32_32x32x16_bf16 v[80:95], v[96:99], v[136:139], v[80:95]
	s_nop 10
	v_exp_f32_e32 v64, v48
	s_nop 0
	s_nop 0
	v_exp_f32_e32 v65, v49
	v_mfma_f32_32x32x16_bf16 v[80:95], v[96:99], v[76:79], v[80:95]
	s_nop 0
	v_exp_f32_e32 v66, v50
	s_nop 0
	s_nop 0
	v_exp_f32_e32 v67, v51
	v_mfma_f32_32x32x16_bf16 v[80:95], v[100:103], v[140:143], v[80:95]
	s_nop 0
	v_exp_f32_e32 v68, v52
	s_nop 0
	s_nop 0
	v_exp_f32_e32 v69, v53
	v_mfma_f32_32x32x16_bf16 v[80:95], v[100:103], v[144:147], v[80:95]
	s_nop 0
	v_exp_f32_e32 v70, v54
	s_nop 0
	s_nop 0
	v_exp_f32_e32 v71, v55
	s_nop 6
	v_exp_f32_e32 v53, v85
	v_add_u32_e32 v85, v198, v200
	ds_read_b64_tr_b16 v[140:141], v85 offset:27648
	ds_read_b64_tr_b16 v[142:143], v85 offset:28800
	s_nop 0
	v_exp_f32_e32 v72, v56
	v_exp_f32_e32 v54, v86
	v_exp_f32_e32 v55, v87
	v_exp_f32_e32 v56, v88
	s_nop 0
	v_exp_f32_e32 v73, v57
	v_exp_f32_e32 v57, v89
	v_cvt_pk_bf16_f32 v86, v64, v65
	v_cvt_pk_bf16_f32 v87, v66, v67
	s_nop 0
	v_exp_f32_e32 v74, v58
	v_cvt_pk_bf16_f32 v88, v68, v69
	v_cvt_pk_bf16_f32 v89, v70, v71
	v_exp_f32_e32 v58, v90
	s_nop 0
	v_exp_f32_e32 v75, v59
	s_waitcnt lgkmcnt(0)
; #define MFMA32(a, b, c) __builtin_amdgcn_mfma_f32_32x32x16_bf16((a), (b), (c), 0, 0, 0)
; DI unsigned pk_bf16(float lo, float hi) { f32x2 v = {lo, hi}; bf2_t b = __builtin_convertvector(v, bf2_t); return __builtin_bit_cast(unsigned, b); }
; DI int crow(int i, int h) { return (i & 3) + 8 * (i >> 2) + 4 * h; }
; DI float fast_exp2(float x) { return __builtin_amdgcn_exp2f(x); }
; template <int DQK, bool SB, bool SMAX>
; DI void attn_item(const Params& p, char* smem, int bh, int qb, float Mb) {
;     ...
;         for (int kb = 0; kb < 2; ++kb)
; #pragma unroll
;           for (int i = 0; i < 16; ++i) {
;             const int key = kb0 + kb * 32 + crow(i, h);
;             const bool valid = !diag || (key < query);
;             st[kb][i] = valid ? fast_exp2(ca[kb][i]) : 0.f;
;           }
;         carry += tsum;
;       }
; #pragma unroll
;       for (int kb = 0; kb < 2; ++kb)
; #pragma unroll
;         for (int s = 0; s < 2; ++s) {
;           u32x4 w;
; #pragma unroll
;           for (int e = 0; e < 4; ++e) w[e] = pk_bf16(st[kb][8 * s + 2 * e], st[kb][8 * s + 2 * e + 1]);
;           pk[kb * 2 + s] = __builtin_bit_cast(bf16x8, w);
;         }
; #pragma unroll
;       for (int kk = 0; kk < 4; ++kk)
; #pragma unroll
;         for (int db = 0; db < 2; ++db) {
;           const s16x4 v0 = __builtin_amdgcn_ds_read_tr16_b64_v4i16((lds_s16x4*)(vc + voff + (16 * kk) * VSTR + 32 * db));
;           const s16x4 v1 = __builtin_amdgcn_ds_read_tr16_b64_v4i16((lds_s16x4*)(vc + voff + (16 * kk + 8) * VSTR + 32 * db));
;           const bf16x8 vf = __builtin_shufflevector(v0, v1, 0, 1, 2, 3, 4, 5, 6, 7);
;           O[db] = MFMA32(vf, pk[kk], O[db]);
;         }
	v_mfma_f32_32x32x16_bf16 v[32:47], v[140:143], v[86:89], v[32:47]
	ds_read_b64_tr_b16 v[140:141], v85 offset:27712
	ds_read_b64_tr_b16 v[142:143], v85 offset:28864
	v_exp_f32_e32 v59, v91
	s_nop 0
	v_exp_f32_e32 v76, v60
	v_exp_f32_e32 v60, v92
	v_cvt_pk_bf16_f32 v90, v72, v73
	v_cvt_pk_bf16_f32 v91, v74, v75
	s_nop 0
	v_exp_f32_e32 v77, v61
	s_waitcnt lgkmcnt(0)
	v_mfma_f32_32x32x16_bf16 v[16:31], v[140:143], v[86:89], v[16:31]
	ds_read_b64_tr_b16 v[86:87], v85 offset:29952
	ds_read_b64_tr_b16 v[88:89], v85 offset:31104
	v_exp_f32_e32 v61, v93
	s_nop 0
	v_exp_f32_e32 v78, v62
	v_cvt_pk_bf16_f32 v92, v76, v77
	v_exp_f32_e32 v49, v81
	v_exp_f32_e32 v50, v82
	s_nop 0
	v_exp_f32_e32 v79, v63
	v_exp_f32_e32 v51, v83
	v_exp_f32_e32 v52, v84
	s_nop 0
	s_nop 0
	v_cvt_pk_bf16_f32 v93, v78, v79
	v_exp_f32_e32 v48, v80
	s_nop 0
	s_waitcnt lgkmcnt(0)
	v_mfma_f32_32x32x16_bf16 v[32:47], v[86:89], v[90:93], v[32:47]
	ds_read_b64_tr_b16 v[86:87], v85 offset:30016
	ds_read_b64_tr_b16 v[88:89], v85 offset:31168
	s_nop 0
	s_nop 0
	s_nop 0
	s_nop 0
	s_nop 0
	s_nop 0
	s_waitcnt lgkmcnt(0)
	v_mfma_f32_32x32x16_bf16 v[16:31], v[86:89], v[90:93], v[16:31]
	ds_read_b64_tr_b16 v[86:87], v85 offset:32256
	ds_read_b64_tr_b16 v[88:89], v85 offset:33408
	v_cvt_pk_bf16_f32 v136, v48, v49
	v_cvt_pk_bf16_f32 v137, v50, v51
	v_cvt_pk_bf16_f32 v138, v52, v53
	v_cvt_pk_bf16_f32 v139, v54, v55
	v_exp_f32_e32 v62, v94
	v_exp_f32_e32 v63, v95
	s_waitcnt lgkmcnt(0)
	v_mfma_f32_32x32x16_bf16 v[32:47], v[86:89], v[136:139], v[32:47]
	ds_read_b64_tr_b16 v[86:87], v85 offset:32320
	ds_read_b64_tr_b16 v[88:89], v85 offset:33472
	s_nop 0
	s_nop 0
	s_nop 0
	s_nop 0
	s_nop 0
	s_nop 0
	s_waitcnt lgkmcnt(0)
	v_mfma_f32_32x32x16_bf16 v[16:31], v[86:89], v[136:139], v[16:31]
	ds_read_b64_tr_b16 v[86:87], v85 offset:34560
	ds_read_b64_tr_b16 v[88:89], v85 offset:35712
	s_nop 0
	s_nop 0
	v_cvt_pk_bf16_f32 v80, v56, v57
	v_cvt_pk_bf16_f32 v81, v58, v59
	v_cvt_pk_bf16_f32 v82, v60, v61
	v_cvt_pk_bf16_f32 v83, v62, v63
	v_add_f32_e32 v84, v184, v185
	v_add_f32_e32 v152, v152, v84
	s_waitcnt lgkmcnt(0)
	v_mfma_f32_32x32x16_bf16 v[32:47], v[86:89], v[80:83], v[32:47]
	ds_read_b64_tr_b16 v[86:87], v85 offset:34624
	ds_read_b64_tr_b16 v[88:89], v85 offset:35776
	s_waitcnt lgkmcnt(0)
	v_mfma_f32_32x32x16_bf16 v[16:31], v[86:89], v[80:83], v[16:31]
